# P0/P2/P6/P8 stores write-through (sc1) and the L2 write-back dropped from their seams
# baseline (speedup 1.0000x reference)
.LBB0_123:
	v_ashrrev_i32_e32 v11, 31, v10
	v_lshlrev_b64 v[16:17], 13, v[10:11]
	v_lshl_add_u64 v[32:33], v[8:9], 0, v[16:17]
	v_add_co_u32_e32 v48, vcc, s12, v32
	global_load_dwordx4 v[16:19], v[32:33], off nt
	global_load_dwordx4 v[20:23], v[32:33], off offset:1024 nt
	global_load_dwordx4 v[24:27], v[32:33], off offset:2048 nt
	global_load_dwordx4 v[28:31], v[32:33], off offset:3072 nt
	v_addc_co_u32_e32 v49, vcc, 0, v33, vcc
	global_load_dwordx4 v[32:35], v[48:49], off nt
	global_load_dwordx4 v[36:39], v[48:49], off offset:1024 nt
	global_load_dwordx4 v[40:43], v[48:49], off offset:2048 nt
	global_load_dwordx4 v[44:47], v[48:49], off offset:3072 nt
	s_waitcnt vmcnt(7)
	v_mul_f32_e32 v64, v17, v17
	s_waitcnt vmcnt(6)
	v_mul_f32_e32 v65, v21, v21
	s_waitcnt vmcnt(5)
	v_mul_f32_e32 v66, v25, v25
	v_fmac_f32_e32 v64, v16, v16
	v_fmac_f32_e32 v65, v20, v20
	s_waitcnt vmcnt(4)
	v_mul_f32_e32 v67, v29, v29
	v_fmac_f32_e32 v66, v24, v24
	s_waitcnt vmcnt(3)
	v_mov_b32_e32 v50, v33
	s_waitcnt vmcnt(2)
	v_mov_b32_e32 v51, v37
	s_waitcnt vmcnt(1)
	v_mov_b32_e32 v58, v41
	s_waitcnt vmcnt(0)
	v_mov_b32_e32 v59, v45
	v_fmac_f32_e32 v64, v18, v18
	v_fmac_f32_e32 v65, v22, v22
	v_fmac_f32_e32 v67, v28, v28
	v_mov_b32_e32 v48, v32
	v_mov_b32_e32 v49, v36
	v_mov_b32_e32 v56, v40
	v_mov_b32_e32 v57, v44
	v_pk_mul_f32 v[50:51], v[50:51], v[50:51]
	v_pk_mul_f32 v[58:59], v[58:59], v[58:59]
	v_fmac_f32_e32 v66, v26, v26
	v_fmac_f32_e32 v64, v19, v19
	v_fmac_f32_e32 v65, v23, v23
	v_mov_b32_e32 v52, v34
	v_mov_b32_e32 v53, v38
	v_fmac_f32_e32 v67, v30, v30
	v_pk_fma_f32 v[48:49], v[48:49], v[48:49], v[50:51]
	v_pk_fma_f32 v[50:51], v[56:57], v[56:57], v[58:59]
	v_fmac_f32_e32 v66, v27, v27
	v_add_f32_e32 v56, v64, v65
	v_mov_b32_e32 v54, v35
	v_mov_b32_e32 v55, v39
	v_fmac_f32_e32 v67, v31, v31
	v_pk_fma_f32 v[48:49], v[52:53], v[52:53], v[48:49]
	v_add_f32_e32 v52, v56, v66
	v_mov_b32_e32 v60, v42
	v_mov_b32_e32 v61, v46
	v_pk_fma_f32 v[48:49], v[54:55], v[54:55], v[48:49]
	v_add_f32_e32 v52, v52, v67
	v_mov_b32_e32 v62, v43
	v_mov_b32_e32 v63, v47
	v_pk_fma_f32 v[50:51], v[60:61], v[60:61], v[50:51]
	v_add_f32_e32 v48, v52, v48
	v_pk_fma_f32 v[50:51], v[62:63], v[62:63], v[50:51]
	v_add_f32_e32 v48, v48, v49
	v_add_f32_e32 v48, v48, v50
	v_add_f32_e32 v48, v48, v51
	ds_bpermute_b32 v49, v1, v48
	s_waitcnt lgkmcnt(0)
	v_add_f32_e32 v48, v48, v49
	ds_bpermute_b32 v49, v3, v48
	s_waitcnt lgkmcnt(0)
	v_add_f32_e32 v48, v48, v49
	ds_bpermute_b32 v49, v5, v48
	s_waitcnt lgkmcnt(0)
	v_add_f32_e32 v48, v48, v49
	ds_bpermute_b32 v49, v12, v48
	s_waitcnt lgkmcnt(0)
	v_add_f32_e32 v48, v48, v49
	ds_bpermute_b32 v49, v13, v48
	s_waitcnt lgkmcnt(0)
	v_add_f32_e32 v50, v48, v49
	ds_bpermute_b32 v51, v14, v50
	v_lshlrev_b64 v[48:49], 12, v[10:11]
	v_add_u32_e32 v10, s3, v10
	v_cmp_lt_i32_e64 s[6:7], s14, v10
	v_lshl_add_u64 v[48:49], v[6:7], 0, v[48:49]
	s_waitcnt lgkmcnt(0)
	v_add_f32_e32 v11, v50, v51
	v_fmamk_f32 v11, v11, 0x3a000000, v15
	v_mul_f32_e32 v50, 0x4b800000, v11
	v_cmp_gt_f32_e32 vcc, s13, v11
	s_or_b64 s[10:11], s[6:7], s[10:11]
	s_nop 0
	v_cndmask_b32_e32 v11, v11, v50, vcc
	v_rsq_f32_e32 v11, v11
	s_nop 0
	v_mul_f32_e32 v50, 0x45800000, v11
	v_cndmask_b32_e32 v50, v11, v50, vcc
	v_pk_mul_f32 v[16:17], v[16:17], v[50:51] op_sel_hi:[1,0]
	v_pk_mul_f32 v[18:19], v[18:19], v[50:51] op_sel_hi:[1,0]
	v_pk_mul_f32 v[20:21], v[20:21], v[50:51] op_sel_hi:[1,0]
	v_pk_mul_f32 v[22:23], v[22:23], v[50:51] op_sel_hi:[1,0]
	v_pk_mul_f32 v[24:25], v[24:25], v[50:51] op_sel_hi:[1,0]
	v_pk_mul_f32 v[26:27], v[26:27], v[50:51] op_sel_hi:[1,0]
	v_pk_mul_f32 v[28:29], v[28:29], v[50:51] op_sel_hi:[1,0]
	v_pk_mul_f32 v[30:31], v[30:31], v[50:51] op_sel_hi:[1,0]
	v_pk_mul_f32 v[32:33], v[32:33], v[50:51] op_sel_hi:[1,0]
	v_pk_mul_f32 v[34:35], v[34:35], v[50:51] op_sel_hi:[1,0]
	v_pk_mul_f32 v[36:37], v[36:37], v[50:51] op_sel_hi:[1,0]
	v_pk_mul_f32 v[38:39], v[38:39], v[50:51] op_sel_hi:[1,0]
	v_pk_mul_f32 v[40:41], v[40:41], v[50:51] op_sel_hi:[1,0]
	v_pk_mul_f32 v[42:43], v[42:43], v[50:51] op_sel_hi:[1,0]
	v_pk_mul_f32 v[44:45], v[44:45], v[50:51] op_sel_hi:[1,0]
	v_pk_mul_f32 v[46:47], v[46:47], v[50:51] op_sel_hi:[1,0]
	v_cvt_pk_bf16_f32 v16, v16, v17
	v_cvt_pk_bf16_f32 v17, v18, v19
	v_cvt_pk_bf16_f32 v18, v20, v21
	v_cvt_pk_bf16_f32 v19, v22, v23
	v_cvt_pk_bf16_f32 v20, v24, v25
	v_cvt_pk_bf16_f32 v21, v26, v27
	v_cvt_pk_bf16_f32 v22, v28, v29
	v_cvt_pk_bf16_f32 v23, v30, v31
	v_cvt_pk_bf16_f32 v24, v32, v33
	v_cvt_pk_bf16_f32 v25, v34, v35
	v_cvt_pk_bf16_f32 v26, v36, v37
	v_cvt_pk_bf16_f32 v27, v38, v39
	v_cvt_pk_bf16_f32 v28, v40, v41
	v_cvt_pk_bf16_f32 v29, v42, v43
	v_cvt_pk_bf16_f32 v30, v44, v45
	v_cvt_pk_bf16_f32 v31, v46, v47
	global_store_dwordx2 v[48:49], v[16:17], off sc1
	global_store_dwordx2 v[48:49], v[18:19], off offset:512 sc1
	global_store_dwordx2 v[48:49], v[20:21], off offset:1024 sc1
	global_store_dwordx2 v[48:49], v[22:23], off offset:1536 sc1
	global_store_dwordx2 v[48:49], v[24:25], off offset:2048 sc1
	global_store_dwordx2 v[48:49], v[26:27], off offset:2560 sc1
	global_store_dwordx2 v[48:49], v[28:29], off offset:3072 sc1
	global_store_dwordx2 v[48:49], v[30:31], off offset:3584 sc1
	s_andn2_b64 exec, exec, s[10:11]
	s_cbranch_execnz .LBB0_123

.LBB0_126:
	v_ashrrev_i32_e32 v1, 31, v0
	v_lshlrev_b64 v[14:15], 13, v[0:1]
	v_lshl_add_u64 v[30:31], v[2:3], 0, v[14:15]
	global_load_dwordx4 v[14:17], v[30:31], off nt
	global_load_dwordx4 v[18:21], v[30:31], off offset:1024 nt
	global_load_dwordx4 v[22:25], v[30:31], off offset:2048 nt
	global_load_dwordx4 v[26:29], v[30:31], off offset:3072 nt
	v_add_co_u32_e32 v46, vcc, s12, v30
	s_waitcnt vmcnt(3)
	v_mul_f32_e32 v13, v15, v15
	v_addc_co_u32_e32 v47, vcc, 0, v31, vcc
	global_load_dwordx4 v[30:33], v[46:47], off nt
	global_load_dwordx4 v[34:37], v[46:47], off offset:1024 nt
	global_load_dwordx4 v[38:41], v[46:47], off offset:2048 nt
	global_load_dwordx4 v[42:45], v[46:47], off offset:3072 nt
	s_waitcnt vmcnt(6)
	v_mul_f32_e32 v62, v19, v19
	s_waitcnt vmcnt(5)
	v_mul_f32_e32 v63, v23, v23
	v_fmac_f32_e32 v13, v14, v14
	v_fmac_f32_e32 v62, v18, v18
	s_waitcnt vmcnt(4)
	v_mul_f32_e32 v64, v27, v27
	v_fmac_f32_e32 v63, v22, v22
	v_fmac_f32_e32 v13, v16, v16
	v_fmac_f32_e32 v62, v20, v20
	v_fmac_f32_e32 v64, v26, v26
	v_fmac_f32_e32 v63, v24, v24
	v_fmac_f32_e32 v13, v17, v17
	v_fmac_f32_e32 v62, v21, v21
	v_fmac_f32_e32 v64, v28, v28
	v_fmac_f32_e32 v63, v25, v25
	v_add_f32_e32 v13, v13, v62
	v_fmac_f32_e32 v64, v29, v29
	v_add_f32_e32 v13, v13, v63
	v_add_f32_e32 v13, v13, v64
	s_waitcnt vmcnt(3)
	v_mov_b32_e32 v48, v31
	s_waitcnt vmcnt(2)
	v_mov_b32_e32 v49, v35
	v_mov_b32_e32 v46, v30
	v_mov_b32_e32 v47, v34
	v_pk_mul_f32 v[48:49], v[48:49], v[48:49]
	v_mov_b32_e32 v50, v32
	v_mov_b32_e32 v51, v36
	s_waitcnt vmcnt(1)
	v_mov_b32_e32 v56, v39
	s_waitcnt vmcnt(0)
	v_mov_b32_e32 v57, v43
	v_pk_fma_f32 v[46:47], v[46:47], v[46:47], v[48:49]
	v_mov_b32_e32 v52, v33
	v_mov_b32_e32 v53, v37
	v_mov_b32_e32 v54, v38
	v_mov_b32_e32 v55, v42
	v_pk_mul_f32 v[56:57], v[56:57], v[56:57]
	v_pk_fma_f32 v[46:47], v[50:51], v[50:51], v[46:47]
	v_mov_b32_e32 v58, v40
	v_mov_b32_e32 v59, v44
	v_pk_fma_f32 v[48:49], v[54:55], v[54:55], v[56:57]
	v_pk_fma_f32 v[46:47], v[52:53], v[52:53], v[46:47]
	v_mov_b32_e32 v60, v41
	v_mov_b32_e32 v61, v45
	v_pk_fma_f32 v[48:49], v[58:59], v[58:59], v[48:49]
	v_add_f32_e32 v13, v13, v46
	v_pk_fma_f32 v[48:49], v[60:61], v[60:61], v[48:49]
	v_add_f32_e32 v13, v13, v47
	v_add_f32_e32 v13, v13, v48
	v_add_f32_e32 v13, v13, v49
	ds_bpermute_b32 v46, v4, v13
	s_waitcnt lgkmcnt(0)
	v_add_f32_e32 v13, v13, v46
	ds_bpermute_b32 v46, v5, v13
	s_waitcnt lgkmcnt(0)
	v_add_f32_e32 v13, v13, v46
	ds_bpermute_b32 v46, v8, v13
	s_waitcnt lgkmcnt(0)
	v_add_f32_e32 v13, v13, v46
	ds_bpermute_b32 v46, v9, v13
	s_waitcnt lgkmcnt(0)
	v_add_f32_e32 v13, v13, v46
	ds_bpermute_b32 v46, v10, v13
	s_waitcnt lgkmcnt(0)
	v_add_f32_e32 v13, v13, v46
	ds_bpermute_b32 v48, v11, v13
	v_lshlrev_b64 v[46:47], 12, v[0:1]
	v_add_u32_e32 v0, s3, v0
	v_cmp_lt_i32_e64 s[6:7], s14, v0
	v_lshl_add_u64 v[46:47], v[6:7], 0, v[46:47]
	s_waitcnt lgkmcnt(0)
	v_add_f32_e32 v1, v13, v48
	v_fmamk_f32 v1, v1, 0x3a000000, v12
	v_mul_f32_e32 v13, 0x4b800000, v1
	v_cmp_gt_f32_e32 vcc, s13, v1
	s_or_b64 s[10:11], s[6:7], s[10:11]
	s_nop 0
	v_cndmask_b32_e32 v1, v1, v13, vcc
	v_rsq_f32_e32 v1, v1
	s_nop 0
	v_mul_f32_e32 v13, 0x45800000, v1
	v_cndmask_b32_e32 v48, v1, v13, vcc
	v_pk_mul_f32 v[14:15], v[14:15], v[48:49] op_sel_hi:[1,0]
	v_pk_mul_f32 v[16:17], v[16:17], v[48:49] op_sel_hi:[1,0]
	v_pk_mul_f32 v[18:19], v[18:19], v[48:49] op_sel_hi:[1,0]
	v_pk_mul_f32 v[20:21], v[20:21], v[48:49] op_sel_hi:[1,0]
	v_pk_mul_f32 v[22:23], v[22:23], v[48:49] op_sel_hi:[1,0]
	v_pk_mul_f32 v[24:25], v[24:25], v[48:49] op_sel_hi:[1,0]
	v_pk_mul_f32 v[26:27], v[26:27], v[48:49] op_sel_hi:[1,0]
	v_pk_mul_f32 v[28:29], v[28:29], v[48:49] op_sel_hi:[1,0]
	v_pk_mul_f32 v[30:31], v[30:31], v[48:49] op_sel_hi:[1,0]
	v_pk_mul_f32 v[32:33], v[32:33], v[48:49] op_sel_hi:[1,0]
	v_pk_mul_f32 v[34:35], v[34:35], v[48:49] op_sel_hi:[1,0]
	v_pk_mul_f32 v[36:37], v[36:37], v[48:49] op_sel_hi:[1,0]
	v_pk_mul_f32 v[38:39], v[38:39], v[48:49] op_sel_hi:[1,0]
	v_pk_mul_f32 v[40:41], v[40:41], v[48:49] op_sel_hi:[1,0]
	v_pk_mul_f32 v[42:43], v[42:43], v[48:49] op_sel_hi:[1,0]
	v_pk_mul_f32 v[44:45], v[44:45], v[48:49] op_sel_hi:[1,0]
	v_cvt_pk_bf16_f32 v14, v14, v15
	v_cvt_pk_bf16_f32 v15, v16, v17
	v_cvt_pk_bf16_f32 v16, v18, v19
	v_cvt_pk_bf16_f32 v17, v20, v21
	v_cvt_pk_bf16_f32 v18, v22, v23
	v_cvt_pk_bf16_f32 v19, v24, v25
	v_cvt_pk_bf16_f32 v20, v26, v27
	v_cvt_pk_bf16_f32 v21, v28, v29
	v_cvt_pk_bf16_f32 v22, v30, v31
	v_cvt_pk_bf16_f32 v23, v32, v33
	v_cvt_pk_bf16_f32 v24, v34, v35
	v_cvt_pk_bf16_f32 v25, v36, v37
	v_cvt_pk_bf16_f32 v26, v38, v39
	v_cvt_pk_bf16_f32 v27, v40, v41
	v_cvt_pk_bf16_f32 v28, v42, v43
	v_cvt_pk_bf16_f32 v29, v44, v45
	global_store_dwordx2 v[46:47], v[14:15], off sc1
	global_store_dwordx2 v[46:47], v[16:17], off offset:512 sc1
	global_store_dwordx2 v[46:47], v[18:19], off offset:1024 sc1
	global_store_dwordx2 v[46:47], v[20:21], off offset:1536 sc1
	global_store_dwordx2 v[46:47], v[22:23], off offset:2048 sc1
	global_store_dwordx2 v[46:47], v[24:25], off offset:2560 sc1
	global_store_dwordx2 v[46:47], v[26:27], off offset:3072 sc1
	global_store_dwordx2 v[46:47], v[28:29], off offset:3584 sc1
	s_andn2_b64 exec, exec, s[10:11]
	s_cbranch_execnz .LBB0_126

.LBB0_147:
	s_or_b64 exec, exec, s[14:15]
	v_cvt_f32_u32_e32 v4, v2
	s_waitcnt vmcnt(0)
	v_readfirstlane_b32 s3, v3
	v_sub_u32_e32 v3, 0, v2
	v_rcp_iflag_f32_e32 v4, v4
	v_add_u32_e32 v5, s3, v1
	v_mul_f32_e32 v4, 0x4f7ffffe, v4
	v_cvt_u32_f32_e32 v4, v4
	v_mul_lo_u32 v1, v3, v4
	v_mul_hi_u32 v1, v4, v1
	v_add_u32_e32 v1, v4, v1
	v_mul_hi_u32 v1, v5, v1
	v_mul_lo_u32 v3, v1, v2
	v_sub_u32_e32 v3, v5, v3
	v_add_u32_e32 v4, 1, v1
	v_cmp_ge_u32_e32 vcc, v3, v2
	s_nop 1
	v_cndmask_b32_e32 v1, v1, v4, vcc
	v_sub_u32_e32 v4, v3, v2
	v_cndmask_b32_e32 v3, v3, v4, vcc
	v_add_u32_e32 v4, 1, v1
	v_cmp_ge_u32_e32 vcc, v3, v2
	v_add_u32_e32 v3, 1, v5
	s_nop 0
	v_cndmask_b32_e32 v1, v1, v4, vcc
	v_mul_lo_u32 v4, v2, v1
	v_add_u32_e32 v2, v4, v2
	v_cmp_ne_u32_e32 vcc, v3, v2
	s_waitcnt lgkmcnt(0)
	s_cbranch_vccnz .Lbk0_poll
	s_nop 0
	s_waitcnt vmcnt(0)
	v_mov_b32_e32 v6, 0x3600
	v_mov_b32_e32 v7, 1
	global_atomic_add v6, v7, s[42:43]

.LBB0_473:
	s_or_b64 exec, exec, s[54:55]
	v_cndmask_b32_e64 v14, 0, v14, s[8:9]
	v_add_f32_e32 v15, v15, v14
	v_cndmask_b32_e64 v14, v14, v15, s[10:11]
	v_add_f32_e32 v15, v16, v14
	v_cndmask_b32_e64 v14, v14, v15, s[12:13]
	v_add_f32_e32 v15, v17, v14
	v_cndmask_b32_e64 v14, v14, v15, s[14:15]
	v_add_f32_e32 v15, v18, v14
	v_cndmask_b32_e64 v14, v14, v15, s[16:17]
	v_add_f32_e32 v15, v19, v14
	v_cndmask_b32_e64 v14, v14, v15, s[18:19]
	v_add_f32_e32 v12, v12, v14
	v_cndmask_b32_e64 v12, v14, v12, s[20:21]
	v_add_f32_e32 v13, v13, v12
	v_or_b32_e32 v20, 0x80, v23
	v_cndmask_b32_e64 v17, v12, v13, s[22:23]
	v_lshlrev_b32_e32 v12, 1, v20
	v_add_f32_e32 v13, v26, v17
	v_add3_u32 v16, 0, v12, v40
	v_mul_f32_e32 v12, 0x3fb8aa3b, v13
	v_exp_f32_e32 v12, v12
	v_and_b32_e32 v202, 31, v22
	v_lshrrev_b32_e32 v180, 5, v23
	ds_read_u16 v14, v16 offset:12288
	ds_read_u16 v15, v16 offset:12688
	ds_read_u16 v18, v16 offset:13088
	ds_read_u16 v19, v16 offset:13488
	ds_read_u16 v22, v16 offset:13888
	ds_read_u16 v23, v16 offset:14288
	ds_read_u16 v26, v16 offset:14688
	ds_read_u16 v35, v16 offset:15088
	s_waitcnt lgkmcnt(7)
	v_lshlrev_b32_e32 v14, 16, v14
	v_mul_f32_e32 v12, v12, v14
	v_cvt_pk_bf16_f32 v12, v12, s0
	ds_write_b16 v16, v12 offset:12288
	v_mul_f32_e32 v12, 0xbfb8aa3b, v13
	v_exp_f32_e32 v36, v12
	v_sub_f32_e32 v12, v21, v13
	v_add_f32_e32 v13, v24, v17
	v_mul_f32_e32 v14, 0x3fb8aa3b, v13
	v_exp_f32_e32 v14, v14
	s_waitcnt lgkmcnt(7)
	v_lshlrev_b32_e32 v15, 16, v15
	v_mul_f32_e32 v12, 0x3fb8aa3b, v12
	v_exp_f32_e32 v12, v12
	v_mul_f32_e32 v14, v14, v15
	v_cvt_pk_bf16_f32 v14, v14, s0
	ds_write_b16 v16, v14 offset:12688
	v_mul_f32_e32 v14, 0xbfb8aa3b, v13
	v_exp_f32_e32 v24, v14
	ds_read_u16 v14, v16 offset:38288
	ds_read_u16 v37, v16 offset:39088
	ds_read_u16 v38, v16 offset:39488
	ds_read_u16 v39, v16 offset:39888
	ds_read_u16 v40, v16 offset:40288
	ds_read_u16 v41, v16 offset:40688
	ds_read_u16 v42, v16 offset:38688
	ds_read_u16 v43, v16 offset:37888
	v_sub_f32_e32 v13, v21, v13
	v_mul_f32_e32 v13, 0x3fb8aa3b, v13
	v_exp_f32_e32 v13, v13
	s_waitcnt lgkmcnt(7)
	v_lshlrev_b32_e32 v15, 16, v14
	s_waitcnt lgkmcnt(0)
	v_lshlrev_b32_e32 v14, 16, v43
	v_mul_f32_e32 v36, v36, v14
	v_cvt_pk_bf16_f32 v36, v36, s0
	v_add_f32_e32 v25, v25, v17
	ds_write_b16 v16, v36 offset:37888
	v_mul_f32_e32 v36, 0x3fb8aa3b, v25
	v_mul_f32_e32 v24, v24, v15
	v_exp_f32_e32 v36, v36
	v_pk_mul_f32 v[12:13], v[12:13], v[14:15]
	v_add_f32_e32 v15, v27, v17
	v_lshlrev_b32_e32 v14, 16, v18
	v_mul_f32_e32 v18, 0x3fb8aa3b, v15
	v_exp_f32_e32 v18, v18
	v_mul_f32_e32 v14, v36, v14
	v_cvt_pk_bf16_f32 v14, v14, s0
	v_lshlrev_b32_e32 v19, 16, v19
	v_cvt_pk_bf16_f32 v24, v24, s0
	ds_write_b16 v16, v14 offset:13088
	v_mul_f32_e32 v14, 0xbfb8aa3b, v25
	v_mul_f32_e32 v18, v18, v19
	ds_write_b16 v16, v24 offset:38288
	v_exp_f32_e32 v24, v14
	v_cvt_pk_bf16_f32 v18, v18, s0
	ds_write_b16 v16, v18 offset:13488
	v_mul_f32_e32 v18, 0xbfb8aa3b, v15
	v_sub_f32_e32 v14, v21, v25
	v_exp_f32_e32 v25, v18
	v_sub_f32_e32 v15, v21, v15
	v_mul_f32_e32 v14, 0x3fb8aa3b, v14
	v_mul_f32_e32 v15, 0x3fb8aa3b, v15
	v_lshlrev_b32_e32 v18, 16, v42
	v_exp_f32_e32 v14, v14
	v_exp_f32_e32 v15, v15
	v_mul_f32_e32 v24, v24, v18
	v_lshlrev_b32_e32 v19, 16, v37
	v_cvt_pk_bf16_f32 v24, v24, s0
	ds_write_b16 v16, v24 offset:38688
	v_mul_f32_e32 v24, v25, v19
	v_add_f32_e32 v25, v28, v17
	v_mul_f32_e32 v27, 0x3fb8aa3b, v25
	v_exp_f32_e32 v27, v27
	v_pk_mul_f32 v[14:15], v[14:15], v[18:19]
	v_add_f32_e32 v19, v29, v17
	v_lshlrev_b32_e32 v18, 16, v22
	v_mul_f32_e32 v22, 0x3fb8aa3b, v19
	v_exp_f32_e32 v22, v22
	v_mul_f32_e32 v18, v27, v18
	v_cvt_pk_bf16_f32 v18, v18, s0
	v_lshlrev_b32_e32 v23, 16, v23
	v_cvt_pk_bf16_f32 v24, v24, s0
	ds_write_b16 v16, v18 offset:13888
	v_mul_f32_e32 v18, 0xbfb8aa3b, v25
	v_mul_f32_e32 v22, v22, v23
	ds_write_b16 v16, v24 offset:39088
	v_exp_f32_e32 v24, v18
	v_cvt_pk_bf16_f32 v22, v22, s0
	ds_write_b16 v16, v22 offset:14288
	v_mul_f32_e32 v22, 0xbfb8aa3b, v19
	v_sub_f32_e32 v18, v21, v25
	v_exp_f32_e32 v25, v22
	v_sub_f32_e32 v19, v21, v19
	v_lshlrev_b32_e32 v22, 16, v38
	v_mul_f32_e32 v18, 0x3fb8aa3b, v18
	v_mul_f32_e32 v19, 0x3fb8aa3b, v19
	v_mul_f32_e32 v24, v24, v22
	v_exp_f32_e32 v18, v18
	v_exp_f32_e32 v19, v19
	v_lshlrev_b32_e32 v23, 16, v39
	v_cvt_pk_bf16_f32 v24, v24, s0
	ds_write_b16 v16, v24 offset:39488
	v_mul_f32_e32 v24, v25, v23
	v_add_f32_e32 v25, v33, v17
	v_mul_f32_e32 v27, 0x3fb8aa3b, v25
	v_exp_f32_e32 v27, v27
	v_add_f32_e32 v17, v34, v17
	v_pk_mul_f32 v[18:19], v[18:19], v[22:23]
	v_mul_f32_e32 v23, 0x3fb8aa3b, v17
	v_exp_f32_e32 v23, v23
	v_lshlrev_b32_e32 v22, 16, v26
	v_cvt_pk_bf16_f32 v24, v24, s0
	v_mul_f32_e32 v22, v27, v22
	ds_write_b16 v16, v24 offset:39888
	v_cvt_pk_bf16_f32 v22, v22, s0
	v_lshlrev_b32_e32 v24, 16, v35
	ds_write_b16 v16, v22 offset:14688
	v_mul_f32_e32 v22, 0xbfb8aa3b, v25
	v_mul_f32_e32 v23, v23, v24
	v_exp_f32_e32 v26, v22
	v_cvt_pk_bf16_f32 v23, v23, s0
	ds_write_b16 v16, v23 offset:15088
	v_mul_f32_e32 v23, 0xbfb8aa3b, v17
	v_sub_f32_e32 v22, v21, v25
	v_exp_f32_e32 v27, v23
	v_sub_f32_e32 v17, v21, v17
	v_mul_f32_e32 v22, 0x3fb8aa3b, v22
	v_mul_f32_e32 v17, 0x3fb8aa3b, v17
	v_lshlrev_b32_e32 v24, 16, v40
	v_exp_f32_e32 v22, v22
	v_exp_f32_e32 v23, v17
	v_mul_f32_e32 v17, v26, v24
	v_lshlrev_b32_e32 v25, 16, v41
	v_cvt_pk_bf16_f32 v17, v17, s0
	ds_write_b16 v16, v17 offset:40288
	v_mul_f32_e32 v17, v27, v25
	v_cvt_pk_bf16_f32 v17, v17, s0
	s_mul_i32 s25, s57, 0x24000
	ds_write_b16 v16, v17 offset:40688
	v_pk_mul_f32 v[16:17], v[22:23], v[24:25]
	s_mul_hi_i32 s24, s57, 0x24000
	s_add_u32 s8, s69, s25
	v_cvt_pk_bf16_f32 v12, v12, v13
	v_cvt_pk_bf16_f32 v13, v14, v15
	v_cvt_pk_bf16_f32 v15, v16, v17
	v_mad_u32_u24 v16, v20, s66, 0
	s_addc_u32 s9, s70, s24
	v_add3_u32 v17, v16, v30, v31
	s_bfe_i32 s10, s59, 0x10006
	v_cvt_pk_bf16_f32 v14, v18, v19
	ds_write_b64 v17, v[12:13] offset:63488
	v_add_u32_e32 v12, v16, v32
	s_and_b32 s12, s10, 3
	ds_write_b64 v12, v[14:15] offset:63488
	v_lshl_add_u32 v16, v180, 4, 0
	v_lshl_or_b32 v12, s12, 5, v202
	v_mad_u32_u24 v203, v12, s66, v16
	s_waitcnt lgkmcnt(0)
	s_barrier
	ds_read_b128 v[12:15], v203 offset:63488
	ds_read_b128 v[204:207], v203 offset:63520
	s_add_i32 s11, s12, 1
	s_waitcnt lgkmcnt(1)
	v_mfma_f32_32x32x16_bf16 v[128:143], v[12:15], v[0:3], 0
	s_add_i32 s10, s12, 2
	v_lshlrev_b32_e32 v180, 3, v180
	s_lshl_b32 s13, s12, 1
	s_add_i32 s57, s57, s46
	s_add_i32 s56, s56, s72
	v_mfma_f32_32x32x16_bf16 v[112:127], v[12:15], v[4:7], 0
	v_mfma_f32_32x32x16_bf16 v[96:111], v[12:15], v[8:11], 0
	v_lshl_or_b32 v12, s11, 5, v202
	v_mad_u32_u24 v220, v12, s66, v16
	ds_read_b128 v[12:15], v220 offset:63488
	ds_read_b128 v[208:211], v220 offset:63520
	s_lshl_b32 s11, s11, 1
	s_waitcnt lgkmcnt(1)
	v_mfma_f32_32x32x16_bf16 v[80:95], v[12:15], v[0:3], 0
	v_mfma_f32_32x32x16_bf16 v[64:79], v[12:15], v[4:7], 0
	v_mfma_f32_32x32x16_bf16 v[48:63], v[12:15], v[8:11], 0
	v_lshl_or_b32 v12, s10, 5, v202
	v_mad_u32_u24 v221, v12, s66, v16
	ds_read_b128 v[12:15], v221 offset:63488
	ds_read_b128 v[216:219], v221 offset:63520
	s_lshl_b32 s10, s10, 1
	s_waitcnt lgkmcnt(1)
	v_mfma_f32_32x32x16_bf16 v[32:47], v[12:15], v[0:3], 0
	v_mfma_f32_32x32x16_bf16 v[16:31], v[12:15], v[4:7], 0
	v_mfma_f32_32x32x16_bf16 v[0:15], v[12:15], v[8:11], 0
	v_mfma_f32_32x32x16_bf16 v[128:143], v[204:207], v[168:171], v[128:143]
	v_mfma_f32_32x32x16_bf16 v[112:127], v[204:207], v[172:175], v[112:127]
	v_mfma_f32_32x32x16_bf16 v[96:111], v[204:207], v[176:179], v[96:111]
	v_mfma_f32_32x32x16_bf16 v[80:95], v[208:211], v[168:171], v[80:95]
	v_mfma_f32_32x32x16_bf16 v[64:79], v[208:211], v[172:175], v[64:79]
	v_mfma_f32_32x32x16_bf16 v[48:63], v[208:211], v[176:179], v[48:63]
	s_waitcnt lgkmcnt(0)
	v_mfma_f32_32x32x16_bf16 v[32:47], v[216:219], v[168:171], v[32:47]
	v_mfma_f32_32x32x16_bf16 v[16:31], v[216:219], v[172:175], v[16:31]
	ds_read_b128 v[168:171], v203 offset:63552
	ds_read_b128 v[172:175], v203 offset:63584
	v_mfma_f32_32x32x16_bf16 v[0:15], v[216:219], v[176:179], v[0:15]
	s_waitcnt lgkmcnt(1)
	v_mfma_f32_32x32x16_bf16 v[128:143], v[168:171], v[156:159], v[128:143]
	v_mfma_f32_32x32x16_bf16 v[112:127], v[168:171], v[160:163], v[112:127]
	v_mfma_f32_32x32x16_bf16 v[96:111], v[168:171], v[164:167], v[96:111]
	ds_read_b128 v[168:171], v220 offset:63552
	ds_read_b128 v[176:179], v220 offset:63584
	s_waitcnt lgkmcnt(1)
	v_mfma_f32_32x32x16_bf16 v[80:95], v[168:171], v[156:159], v[80:95]
	v_mfma_f32_32x32x16_bf16 v[64:79], v[168:171], v[160:163], v[64:79]
	v_mfma_f32_32x32x16_bf16 v[48:63], v[168:171], v[164:167], v[48:63]
	ds_read_b128 v[168:171], v221 offset:63552
	ds_read_b128 v[204:207], v221 offset:63584
	s_waitcnt lgkmcnt(1)
	v_mfma_f32_32x32x16_bf16 v[32:47], v[168:171], v[156:159], v[32:47]
	v_mfma_f32_32x32x16_bf16 v[16:31], v[168:171], v[160:163], v[16:31]
	ds_read_b128 v[156:159], v187 offset:37888
	ds_read_b128 v[160:163], v187 offset:12288
	s_waitcnt lgkmcnt(1)
	global_store_dwordx4 v[190:191], v[156:159], off offset:1536 sc1
	v_mfma_f32_32x32x16_bf16 v[128:143], v[172:175], v[148:151], v[128:143]
	v_mfma_f32_32x32x16_bf16 v[0:15], v[168:171], v[164:167], v[0:15]
	ds_read_b128 v[156:159], v189 offset:37888
	ds_read_b128 v[164:167], v189 offset:12288
	s_waitcnt lgkmcnt(2)
	global_store_dwordx4 v[190:191], v[160:163], off sc1
	ds_read_b128 v[160:163], v201 offset:37888
	ds_read_b128 v[168:171], v201 offset:12288
	s_nop 4
	v_cvt_pk_bf16_f32 v128, v128, v129
	s_waitcnt lgkmcnt(3)
	global_store_dwordx4 v[192:193], v[156:159], off offset:1536 sc1
	v_cvt_pk_bf16_f32 v129, v130, v131
	s_waitcnt lgkmcnt(2)
	global_store_dwordx4 v[192:193], v[164:167], off sc1
	s_waitcnt lgkmcnt(1)
	global_store_dwordx4 v[194:195], v[160:163], off offset:1536 sc1
	s_waitcnt lgkmcnt(0)
	global_store_dwordx4 v[194:195], v[168:171], off sc1
	v_lshl_add_u64 v[156:157], s[8:9], 0, v[180:181]
	s_mul_i32 s8, s58, 36
	s_add_i32 s9, s13, s8
	v_mfma_f32_32x32x16_bf16 v[112:127], v[172:175], v[152:155], v[112:127]
	v_lshl_or_b32 v130, s9, 6, v202
	v_ashrrev_i32_e32 v131, 31, v130
	v_lshl_add_u64 v[158:159], v[130:131], 4, v[156:157]
	global_store_dwordx2 v[158:159], v[128:129], off sc1
	v_cvt_pk_bf16_f32 v128, v132, v133
	v_or_b32_e32 v132, 32, v130
	v_ashrrev_i32_e32 v133, 31, v132
	v_cvt_pk_bf16_f32 v129, v134, v135
	v_lshl_add_u64 v[132:133], v[132:133], 4, v[156:157]
	global_store_dwordx2 v[132:133], v[128:129], off sc1
	v_or_b32_e32 v132, 64, v130
	s_add_i32 s9, s8, 12
	v_ashrrev_i32_e32 v133, 31, v132
	v_or_b32_e32 v130, 0x60, v130
	s_add_i32 s12, s13, s9
	v_mfma_f32_32x32x16_bf16 v[96:111], v[172:175], v[144:147], v[96:111]
	v_cvt_pk_bf16_f32 v128, v136, v137
	v_cvt_pk_bf16_f32 v129, v138, v139
	v_lshl_add_u64 v[132:133], v[132:133], 4, v[156:157]
	v_ashrrev_i32_e32 v131, 31, v130
	v_cvt_pk_bf16_f32 v112, v112, v113
	v_cvt_pk_bf16_f32 v113, v114, v115
	v_lshl_or_b32 v114, s12, 6, v202
	global_store_dwordx2 v[132:133], v[128:129], off sc1
	v_cvt_pk_bf16_f32 v128, v140, v141
	v_cvt_pk_bf16_f32 v129, v142, v143
	v_lshl_add_u64 v[130:131], v[130:131], 4, v[156:157]
	v_ashrrev_i32_e32 v115, 31, v114
	global_store_dwordx2 v[130:131], v[128:129], off sc1
	v_lshl_add_u64 v[128:129], v[114:115], 4, v[156:157]
	global_store_dwordx2 v[128:129], v[112:113], off sc1
	v_cvt_pk_bf16_f32 v112, v116, v117
	v_or_b32_e32 v116, 32, v114
	v_ashrrev_i32_e32 v117, 31, v116
	v_cvt_pk_bf16_f32 v113, v118, v119
	v_lshl_add_u64 v[116:117], v[116:117], 4, v[156:157]
	global_store_dwordx2 v[116:117], v[112:113], off sc1
	v_or_b32_e32 v116, 64, v114
	s_add_i32 s12, s8, 24
	v_ashrrev_i32_e32 v117, 31, v116
	v_or_b32_e32 v114, 0x60, v114
	s_add_i32 s13, s13, s12
	v_mfma_f32_32x32x16_bf16 v[80:95], v[176:179], v[148:151], v[80:95]
	v_cvt_pk_bf16_f32 v112, v120, v121
	v_cvt_pk_bf16_f32 v113, v122, v123
	v_lshl_add_u64 v[116:117], v[116:117], 4, v[156:157]
	v_ashrrev_i32_e32 v115, 31, v114
	v_cvt_pk_bf16_f32 v96, v96, v97
	v_cvt_pk_bf16_f32 v97, v98, v99
	v_lshl_or_b32 v98, s13, 6, v202
	global_store_dwordx2 v[116:117], v[112:113], off sc1
	v_cvt_pk_bf16_f32 v112, v124, v125
	v_cvt_pk_bf16_f32 v113, v126, v127
	v_lshl_add_u64 v[114:115], v[114:115], 4, v[156:157]
	v_ashrrev_i32_e32 v99, 31, v98
	global_store_dwordx2 v[114:115], v[112:113], off sc1
	v_lshl_add_u64 v[112:113], v[98:99], 4, v[156:157]
	global_store_dwordx2 v[112:113], v[96:97], off sc1
	v_cvt_pk_bf16_f32 v96, v100, v101
	v_or_b32_e32 v100, 32, v98
	v_ashrrev_i32_e32 v101, 31, v100
	v_cvt_pk_bf16_f32 v97, v102, v103
	v_lshl_add_u64 v[100:101], v[100:101], 4, v[156:157]
	global_store_dwordx2 v[100:101], v[96:97], off sc1
	v_or_b32_e32 v100, 64, v98
	v_ashrrev_i32_e32 v101, 31, v100
	v_or_b32_e32 v98, 0x60, v98
	s_add_i32 s13, s11, s8
	v_mfma_f32_32x32x16_bf16 v[64:79], v[176:179], v[152:155], v[64:79]
	v_cvt_pk_bf16_f32 v96, v104, v105
	v_cvt_pk_bf16_f32 v97, v106, v107
	v_lshl_add_u64 v[100:101], v[100:101], 4, v[156:157]
	v_ashrrev_i32_e32 v99, 31, v98
	v_cvt_pk_bf16_f32 v80, v80, v81
	v_cvt_pk_bf16_f32 v81, v82, v83
	v_lshl_or_b32 v82, s13, 6, v202
	global_store_dwordx2 v[100:101], v[96:97], off sc1
	v_cvt_pk_bf16_f32 v96, v108, v109
	v_cvt_pk_bf16_f32 v97, v110, v111
	v_lshl_add_u64 v[98:99], v[98:99], 4, v[156:157]
	v_ashrrev_i32_e32 v83, 31, v82
	global_store_dwordx2 v[98:99], v[96:97], off sc1
	v_lshl_add_u64 v[96:97], v[82:83], 4, v[156:157]
	global_store_dwordx2 v[96:97], v[80:81], off sc1
	v_cvt_pk_bf16_f32 v80, v84, v85
	v_or_b32_e32 v84, 32, v82
	v_ashrrev_i32_e32 v85, 31, v84
	v_cvt_pk_bf16_f32 v81, v86, v87
	v_lshl_add_u64 v[84:85], v[84:85], 4, v[156:157]
	global_store_dwordx2 v[84:85], v[80:81], off sc1
	v_or_b32_e32 v84, 64, v82
	v_ashrrev_i32_e32 v85, 31, v84
	v_or_b32_e32 v82, 0x60, v82
	s_add_i32 s13, s11, s9
	v_mfma_f32_32x32x16_bf16 v[48:63], v[176:179], v[144:147], v[48:63]
	v_cvt_pk_bf16_f32 v80, v88, v89
	v_cvt_pk_bf16_f32 v81, v90, v91
	v_lshl_add_u64 v[84:85], v[84:85], 4, v[156:157]
	v_ashrrev_i32_e32 v83, 31, v82
	v_cvt_pk_bf16_f32 v64, v64, v65
	v_cvt_pk_bf16_f32 v65, v66, v67
	v_lshl_or_b32 v66, s13, 6, v202
	global_store_dwordx2 v[84:85], v[80:81], off sc1
	v_cvt_pk_bf16_f32 v80, v92, v93
	v_cvt_pk_bf16_f32 v81, v94, v95
	v_lshl_add_u64 v[82:83], v[82:83], 4, v[156:157]
	v_ashrrev_i32_e32 v67, 31, v66
	global_store_dwordx2 v[82:83], v[80:81], off sc1
	v_lshl_add_u64 v[80:81], v[66:67], 4, v[156:157]
	global_store_dwordx2 v[80:81], v[64:65], off sc1
	v_cvt_pk_bf16_f32 v64, v68, v69
	v_or_b32_e32 v68, 32, v66
	v_ashrrev_i32_e32 v69, 31, v68
	v_cvt_pk_bf16_f32 v65, v70, v71
	v_lshl_add_u64 v[68:69], v[68:69], 4, v[156:157]
	global_store_dwordx2 v[68:69], v[64:65], off sc1
	v_or_b32_e32 v68, 64, v66
	v_ashrrev_i32_e32 v69, 31, v68
	v_or_b32_e32 v66, 0x60, v66
	s_add_i32 s11, s11, s12
	v_mfma_f32_32x32x16_bf16 v[32:47], v[204:207], v[148:151], v[32:47]
	v_cvt_pk_bf16_f32 v64, v72, v73
	v_cvt_pk_bf16_f32 v65, v74, v75
	v_lshl_add_u64 v[68:69], v[68:69], 4, v[156:157]
	v_ashrrev_i32_e32 v67, 31, v66
	v_cvt_pk_bf16_f32 v48, v48, v49
	v_cvt_pk_bf16_f32 v49, v50, v51
	v_lshl_or_b32 v50, s11, 6, v202
	global_store_dwordx2 v[68:69], v[64:65], off sc1
	v_cvt_pk_bf16_f32 v64, v76, v77
	v_cvt_pk_bf16_f32 v65, v78, v79
	v_lshl_add_u64 v[66:67], v[66:67], 4, v[156:157]
	v_ashrrev_i32_e32 v51, 31, v50
	global_store_dwordx2 v[66:67], v[64:65], off sc1
	v_lshl_add_u64 v[64:65], v[50:51], 4, v[156:157]
	global_store_dwordx2 v[64:65], v[48:49], off sc1
	v_cvt_pk_bf16_f32 v48, v52, v53
	v_or_b32_e32 v52, 32, v50
	v_ashrrev_i32_e32 v53, 31, v52
	v_cvt_pk_bf16_f32 v49, v54, v55
	v_lshl_add_u64 v[52:53], v[52:53], 4, v[156:157]
	global_store_dwordx2 v[52:53], v[48:49], off sc1
	v_or_b32_e32 v52, 64, v50
	v_ashrrev_i32_e32 v53, 31, v52
	v_or_b32_e32 v50, 0x60, v50
	s_add_i32 s8, s10, s8
	v_mfma_f32_32x32x16_bf16 v[16:31], v[204:207], v[152:155], v[16:31]
	v_cvt_pk_bf16_f32 v48, v56, v57
	v_cvt_pk_bf16_f32 v49, v58, v59
	v_lshl_add_u64 v[52:53], v[52:53], 4, v[156:157]
	v_ashrrev_i32_e32 v51, 31, v50
	v_cvt_pk_bf16_f32 v32, v32, v33
	v_cvt_pk_bf16_f32 v33, v34, v35
	v_lshl_or_b32 v34, s8, 6, v202
	global_store_dwordx2 v[52:53], v[48:49], off sc1
	v_cvt_pk_bf16_f32 v48, v60, v61
	v_cvt_pk_bf16_f32 v49, v62, v63
	v_lshl_add_u64 v[50:51], v[50:51], 4, v[156:157]
	v_ashrrev_i32_e32 v35, 31, v34
	global_store_dwordx2 v[50:51], v[48:49], off sc1
	v_lshl_add_u64 v[48:49], v[34:35], 4, v[156:157]
	global_store_dwordx2 v[48:49], v[32:33], off sc1
	v_cvt_pk_bf16_f32 v32, v36, v37
	v_or_b32_e32 v36, 32, v34
	v_ashrrev_i32_e32 v37, 31, v36
	v_cvt_pk_bf16_f32 v33, v38, v39
	v_lshl_add_u64 v[36:37], v[36:37], 4, v[156:157]
	global_store_dwordx2 v[36:37], v[32:33], off sc1
	v_or_b32_e32 v36, 64, v34
	v_ashrrev_i32_e32 v37, 31, v36
	v_or_b32_e32 v34, 0x60, v34
	s_add_i32 s8, s10, s9
	v_mfma_f32_32x32x16_bf16 v[0:15], v[204:207], v[144:147], v[0:15]
	v_cvt_pk_bf16_f32 v32, v40, v41
	v_cvt_pk_bf16_f32 v33, v42, v43
	v_lshl_add_u64 v[36:37], v[36:37], 4, v[156:157]
	v_ashrrev_i32_e32 v35, 31, v34
	v_cvt_pk_bf16_f32 v16, v16, v17
	v_cvt_pk_bf16_f32 v17, v18, v19
	v_lshl_or_b32 v18, s8, 6, v202
	global_store_dwordx2 v[36:37], v[32:33], off sc1
	v_cvt_pk_bf16_f32 v32, v44, v45
	v_cvt_pk_bf16_f32 v33, v46, v47
	v_lshl_add_u64 v[34:35], v[34:35], 4, v[156:157]
	v_ashrrev_i32_e32 v19, 31, v18
	global_store_dwordx2 v[34:35], v[32:33], off sc1
	v_lshl_add_u64 v[32:33], v[18:19], 4, v[156:157]
	global_store_dwordx2 v[32:33], v[16:17], off sc1
	v_cvt_pk_bf16_f32 v16, v20, v21
	v_or_b32_e32 v20, 32, v18
	v_ashrrev_i32_e32 v21, 31, v20
	v_cvt_pk_bf16_f32 v17, v22, v23
	v_lshl_add_u64 v[20:21], v[20:21], 4, v[156:157]
	global_store_dwordx2 v[20:21], v[16:17], off sc1
	v_or_b32_e32 v20, 64, v18
	v_ashrrev_i32_e32 v21, 31, v20
	v_or_b32_e32 v18, 0x60, v18
	s_add_i32 s10, s10, s12
	v_cvt_pk_bf16_f32 v16, v24, v25
	v_cvt_pk_bf16_f32 v17, v26, v27
	v_lshl_add_u64 v[20:21], v[20:21], 4, v[156:157]
	v_ashrrev_i32_e32 v19, 31, v18
	v_cvt_pk_bf16_f32 v0, v0, v1
	v_cvt_pk_bf16_f32 v1, v2, v3
	v_lshl_or_b32 v2, s10, 6, v202
	global_store_dwordx2 v[20:21], v[16:17], off sc1
	v_cvt_pk_bf16_f32 v16, v28, v29
	v_cvt_pk_bf16_f32 v17, v30, v31
	v_lshl_add_u64 v[18:19], v[18:19], 4, v[156:157]
	v_ashrrev_i32_e32 v3, 31, v2
	global_store_dwordx2 v[18:19], v[16:17], off sc1
	v_lshl_add_u64 v[16:17], v[2:3], 4, v[156:157]
	global_store_dwordx2 v[16:17], v[0:1], off sc1
	v_cvt_pk_bf16_f32 v0, v4, v5
	v_or_b32_e32 v4, 32, v2
	v_ashrrev_i32_e32 v5, 31, v4
	v_cvt_pk_bf16_f32 v1, v6, v7
	v_lshl_add_u64 v[4:5], v[4:5], 4, v[156:157]
	global_store_dwordx2 v[4:5], v[0:1], off sc1
	v_or_b32_e32 v4, 64, v2
	v_ashrrev_i32_e32 v5, 31, v4
	v_or_b32_e32 v2, 0x60, v2
	v_cvt_pk_bf16_f32 v0, v8, v9
	v_cvt_pk_bf16_f32 v1, v10, v11
	v_lshl_add_u64 v[4:5], v[4:5], 4, v[156:157]
	v_ashrrev_i32_e32 v3, 31, v2
	global_store_dwordx2 v[4:5], v[0:1], off sc1
	v_cvt_pk_bf16_f32 v0, v12, v13
	v_cvt_pk_bf16_f32 v1, v14, v15
	v_lshl_add_u64 v[2:3], v[2:3], 4, v[156:157]
	s_cmpk_gt_i32 s57, 0x3ff
	global_store_dwordx2 v[2:3], v[0:1], off sc1
	s_barrier
	s_cbranch_scc1 .LBB0_411
.LBB0_474:
	s_ashr_i32 s8, s57, 8
	s_ashr_i32 s9, s8, 31
	v_mov_b32_e32 v22, v213
	s_lshl_b64 s[8:9], s[8:9], 12
	s_and_b32 s10, s56, 0xfc0
	s_or_b32 s8, s8, s10
	v_ashrrev_i32_e32 v2, 4, v22
	v_ashrrev_i32_e32 v3, 31, v2
	v_and_b32_e32 v23, 63, v22
	v_lshl_add_u64 v[2:3], s[8:9], 0, v[2:3]
	v_mov_b64_e32 v[20:21], s[26:27]
	v_lshlrev_b32_e32 v180, 4, v23
	v_and_b32_e32 v6, 15, v22
	v_mad_u64_u32 v[4:5], s[10:11], v2, s73, v[20:21]
	v_lshl_add_u64 v[0:1], s[34:35], 0, v[180:181]
	v_mad_i32_i24 v5, v3, s73, v5
	v_lshlrev_b32_e32 v180, 1, v6
	v_add_u32_e32 v24, 0x200, v22
	v_lshl_add_u64 v[2:3], v[4:5], 0, v[180:181]
	v_ashrrev_i32_e32 v4, 4, v24
	v_ashrrev_i32_e32 v5, 31, v4
	v_lshl_add_u64 v[4:5], s[8:9], 0, v[4:5]
	v_mad_u64_u32 v[6:7], s[10:11], v4, s73, v[20:21]
	v_add_co_u32_e32 v2, vcc, s75, v2
	v_mad_i32_i24 v7, v5, s73, v7
	s_nop 0
	v_addc_co_u32_e32 v3, vcc, 0, v3, vcc
	v_lshl_add_u64 v[4:5], v[6:7], 0, v[180:181]
	v_add_co_u32_e32 v4, vcc, s75, v4
	v_readfirstlane_b32 s59, v22
	s_nop 0
	v_addc_co_u32_e32 v5, vcc, 0, v5, vcc
	global_load_ushort v18, v[2:3], off
	global_load_ushort v19, v[4:5], off
	s_and_b32 s10, s57, 3
	s_ashr_i32 s58, s59, 7
	s_mul_i32 s12, s10, 12
	s_mul_i32 s13, s58, 3
	s_add_i32 s12, s13, s12
	s_ashr_i32 s13, s12, 31
	s_lshl_b64 s[12:13], s[12:13], 20
	s_mul_i32 s18, s10, 0xc0
	s_lshl_b64 s[10:11], s[8:9], 6
	v_lshl_add_u64 v[0:1], v[0:1], 0, s[12:13]
	v_mul_hi_i32 v2, v22, s81
	v_lshl_add_u64 v[4:5], v[0:1], 0, s[10:11]
	s_mov_b64 s[10:11], 0x100000
	v_lshrrev_b32_e32 v3, 31, v2
	v_ashrrev_i32_e32 v2, 2, v2
	v_lshl_add_u64 v[8:9], v[4:5], 0, s[10:11]
	s_mov_b32 s10, 0x100000
	v_add_u32_e32 v12, v2, v3
	v_add_co_u32_e32 v6, vcc, s10, v4
	s_mov_b64 s[10:11], 0x200000
	v_mul_lo_u32 v2, v12, 24
	v_ashrrev_i32_e32 v13, 31, v12
	v_addc_co_u32_e32 v7, vcc, 0, v5, vcc
	v_lshl_add_u64 v[16:17], v[4:5], 0, s[10:11]
	s_mov_b32 s10, 0x200000
	v_sub_u32_e32 v48, v22, v2
	v_lshl_add_u64 v[2:3], s[8:9], 0, v[12:13]
	v_add_co_u32_e32 v10, vcc, s10, v4
	v_mad_u64_u32 v[14:15], s[14:15], v2, s73, v[20:21]
	s_nop 0
	v_addc_co_u32_e32 v11, vcc, 0, v5, vcc
	v_lshl_add_u32 v25, v22, 2, 0
	v_mad_i32_i24 v15, v3, s73, v15
	global_load_dwordx4 v[0:3], v[4:5], off
	global_load_dwordx4 v[168:171], v[4:5], off offset:1024
	global_load_dwordx4 v[156:159], v[4:5], off offset:2048
	global_load_dwordx4 v[148:151], v[4:5], off offset:3072
	global_load_dwordx4 v[172:175], v[8:9], off offset:1024
	global_load_dwordx4 v[160:163], v[8:9], off offset:2048
	s_nop 0
	global_load_dwordx4 v[4:7], v[6:7], off
	s_nop 0
	global_load_dwordx4 v[152:155], v[8:9], off offset:3072
	global_load_dwordx4 v[176:179], v[16:17], off offset:1024
	global_load_dwordx4 v[164:167], v[16:17], off offset:2048
	s_nop 0
	global_load_dwordx4 v[8:11], v[10:11], off
	s_nop 0
	global_load_dwordx4 v[144:147], v[16:17], off offset:3072
	s_mul_i32 s17, s57, 0x300
	s_mul_hi_i32 s16, s57, 0x300
	s_add_u32 s52, s67, s17
	s_addc_u32 s53, s68, s16
	s_lshl_b32 s28, s18, 1
	v_lshl_add_u64 v[14:15], v[14:15], 0, s[28:29]
	v_mul_lo_u32 v53, v12, s83
	s_lshl_b32 s12, s18, 2
	v_lshlrev_b32_e32 v180, 2, v23
	s_waitcnt vmcnt(0)
	v_lshlrev_b32_e32 v13, 16, v18
	v_lshlrev_b32_e32 v16, 16, v19
	ds_write2st64_b32 v25, v13, v16 offset1:8
	v_mul_hi_i32 v25, v24, s81
	v_lshrrev_b32_e32 v26, 31, v25
	v_ashrrev_i32_e32 v25, 2, v25
	v_add_u32_e32 v32, v25, v26
	v_mul_lo_u32 v25, v32, 24
	v_ashrrev_i32_e32 v33, 31, v32
	v_sub_u32_e32 v54, v24, v25
	v_lshl_add_u64 v[24:25], s[8:9], 0, v[32:33]
	v_add_u32_e32 v33, 0x400, v22
	v_mul_hi_i32 v34, v33, s81
	v_lshlrev_b32_e32 v16, 3, v48
	v_lshrrev_b32_e32 v35, 31, v34
	v_ashrrev_i32_e32 v34, 2, v34
	v_ashrrev_i32_e32 v17, 31, v16
	v_add_u32_e32 v42, v34, v35
	v_lshl_add_u64 v[190:191], v[16:17], 1, v[14:15]
	v_mul_lo_u32 v34, v42, 24
	v_ashrrev_i32_e32 v43, 31, v42
	global_load_dwordx4 v[12:15], v[190:191], off offset:1536
	global_load_dwordx4 v[16:19], v[190:191], off
	v_mad_u64_u32 v[26:27], s[10:11], v24, s73, v[20:21]
	v_sub_u32_e32 v57, v33, v34
	v_lshl_add_u64 v[34:35], s[8:9], 0, v[42:43]
	v_mad_i32_i24 v27, v25, s73, v27
	v_mad_u64_u32 v[20:21], s[8:9], v34, s73, v[20:21]
	v_lshl_add_u64 v[24:25], v[26:27], 0, s[28:29]
	v_lshlrev_b32_e32 v26, 3, v54
	v_mad_i32_i24 v21, v35, s73, v21
	v_lshlrev_b32_e32 v34, 3, v57
	v_ashrrev_i32_e32 v27, 31, v26
	v_lshl_add_u64 v[20:21], v[20:21], 0, s[28:29]
	v_ashrrev_i32_e32 v35, 31, v34
	v_lshl_add_u64 v[192:193], v[26:27], 1, v[24:25]
	v_lshl_add_u64 v[194:195], v[34:35], 1, v[20:21]
	global_load_dwordx4 v[24:27], v[192:193], off offset:1536
	global_load_dwordx4 v[28:31], v[192:193], off
	s_load_dwordx4 s[8:11], s[0:1], 0x28
	global_load_dwordx4 v[34:37], v[194:195], off offset:1536
	global_load_dwordx4 v[38:41], v[194:195], off
	v_add_u32_e32 v20, 0, v53
	v_lshlrev_b32_e32 v43, 4, v48
	v_add_u32_e32 v187, v20, v43
	s_waitcnt lgkmcnt(0)
	s_add_u32 s8, s8, s12
	s_addc_u32 s9, s9, 0
	v_lshl_add_u64 v[44:45], s[8:9], 0, v[180:181]
	s_add_u32 s10, s10, s12
	s_movk_i32 s12, 0x1000
	v_add_co_u32_e32 v46, vcc, s12, v44
	s_movk_i32 s12, 0x3000
	s_nop 0
	v_addc_co_u32_e32 v47, vcc, 0, v45, vcc
	v_add_co_u32_e32 v84, vcc, s75, v44
	s_addc_u32 s11, s11, 0
	s_nop 0
	v_addc_co_u32_e32 v85, vcc, 0, v45, vcc
	v_add_co_u32_e32 v86, vcc, s12, v44
	s_movk_i32 s12, 0x4000
	s_nop 0
	v_addc_co_u32_e32 v87, vcc, 0, v45, vcc
	v_add_co_u32_e32 v88, vcc, s12, v44
	s_movk_i32 s12, 0x5000
	s_nop 0
	v_addc_co_u32_e32 v89, vcc, 0, v45, vcc
	v_add_co_u32_e32 v90, vcc, s12, v44
	global_load_dword v21, v180, s[10:11]
	global_load_dword v33, v180, s[8:9]
	global_load_dword v49, v180, s[8:9] offset:3072
	v_addc_co_u32_e32 v91, vcc, 0, v45, vcc
	s_movk_i32 s12, 0x6000
	v_add_co_u32_e32 v92, vcc, s12, v44
	global_load_dword v52, v[46:47], off offset:2048
	global_load_dword v51, v[84:85], off offset:1024
	global_load_dword v50, v[86:87], off
	v_addc_co_u32_e32 v93, vcc, 0, v45, vcc
	s_movk_i32 s12, 0x7000
	global_load_dword v58, v[86:87], off offset:3072
	global_load_dword v55, v[88:89], off offset:2048
	global_load_dword v56, v[90:91], off offset:1024
	v_add_co_u32_e32 v94, vcc, s12, v44
	s_mov_b32 s12, 0x8000
	s_nop 0
	v_addc_co_u32_e32 v95, vcc, 0, v45, vcc
	global_load_dword v59, v[92:93], off
	global_load_dword v62, v[92:93], off offset:3072
	v_add_co_u32_e32 v96, vcc, s12, v44
	s_mov_b32 s12, 0x9000
	s_nop 0
	v_addc_co_u32_e32 v97, vcc, 0, v45, vcc
	v_add_co_u32_e32 v98, vcc, s12, v44
	s_mov_b32 s12, 0xa000
	s_nop 0
	v_addc_co_u32_e32 v99, vcc, 0, v45, vcc
	global_load_dword v79, v[94:95], off offset:2048
	global_load_dword v77, v[96:97], off offset:1024
	global_load_dword v75, v[98:99], off
	global_load_dword v80, v[98:99], off offset:3072
	v_add_co_u32_e32 v100, vcc, s12, v44
	s_mov_b32 s12, 0xb000
	s_nop 0
	v_addc_co_u32_e32 v101, vcc, 0, v45, vcc
	v_add_co_u32_e32 v44, vcc, s12, v44
	s_nop 1
	v_addc_co_u32_e32 v45, vcc, 0, v45, vcc
	global_load_dword v81, v[100:101], off offset:2048
	global_load_dword v82, v[44:45], off offset:1024
	s_waitcnt vmcnt(22)
	ds_write_b128 v187, v[12:15] offset:37888
	s_waitcnt vmcnt(21)
	ds_write_b128 v187, v[16:19] offset:12288
	v_mul_lo_u32 v12, v32, s83
	v_add_u32_e32 v12, 0, v12
	v_lshlrev_b32_e32 v13, 4, v54
	v_add_u32_e32 v189, v12, v13
	v_mul_lo_u32 v12, v42, s83
	v_add_u32_e32 v12, 0, v12
	v_lshlrev_b32_e32 v13, 4, v57
	v_add_u32_e32 v201, v12, v13
	s_waitcnt vmcnt(20)
	ds_write_b128 v189, v[24:27] offset:37888
	s_waitcnt vmcnt(19)
	ds_write_b128 v189, v[28:31] offset:12288
	s_waitcnt vmcnt(18)
	ds_write_b128 v201, v[34:37] offset:37888
	s_waitcnt vmcnt(17)
	ds_write_b128 v201, v[38:41] offset:12288
	global_load_dword v67, v180, s[10:11] offset:256
	global_load_dword v78, v180, s[8:9] offset:3328
	global_load_dword v76, v180, s[8:9] offset:256
	global_load_dword v74, v[46:47], off offset:2304
	global_load_dword v72, v[84:85], off offset:1280
	global_load_dword v70, v[86:87], off offset:256
	global_load_dword v73, v[86:87], off offset:3328
	global_load_dword v71, v[88:89], off offset:2304
	global_load_dword v68, v[90:91], off offset:1280
	global_load_dword v65, v[92:93], off offset:256
	global_load_dword v69, v[92:93], off offset:3328
	global_load_dword v66, v[94:95], off offset:2304
	global_load_dword v63, v[96:97], off offset:1280
	global_load_dword v60, v[98:99], off offset:256
	global_load_dword v64, v[98:99], off offset:3328
	global_load_dword v61, v[100:101], off offset:2304
	global_load_dword v57, v[44:45], off offset:1280
	global_load_dword v12, v180, s[10:11] offset:512
	global_load_dword v30, v[84:85], off offset:1536
	global_load_dword v43, v[46:47], off offset:2560
	global_load_dword v16, v[88:89], off offset:2560
	s_nop 0
	global_load_dword v47, v[86:87], off offset:3584
	global_load_dword v34, v[86:87], off offset:512
	global_load_dword v19, v[92:93], off offset:3584
	global_load_dword v17, v[92:93], off offset:512
	global_load_dword v48, v[90:91], off offset:1536
	global_load_dword v15, v[96:97], off offset:1536
	global_load_dword v31, v[94:95], off offset:2560
	global_load_dword v14, v[100:101], off offset:2560
	global_load_dword v32, v[98:99], off offset:3584
	global_load_dword v20, v[98:99], off offset:512
	global_load_dword v54, v180, s[8:9] offset:3584
	global_load_dword v53, v180, s[8:9] offset:512
	global_load_dword v18, v[44:45], off offset:1536
	v_ashrrev_i32_e32 v40, 6, v22
	v_lshl_add_u32 v84, v40, 9, 0
	s_waitcnt lgkmcnt(0)
	s_barrier
	ds_read_b128 v[24:27], v84
	ds_read_b128 v[36:39], v84 offset:16
	ds_read_b128 v[86:89], v84 offset:32
	ds_read_b128 v[90:93], v84 offset:48
	s_waitcnt vmcnt(48) lgkmcnt(3)
	v_mul_f32_e32 v13, v49, v25
	v_fmac_f32_e32 v13, v33, v24
	s_waitcnt vmcnt(47)
	v_fmac_f32_e32 v13, v52, v26
	s_waitcnt vmcnt(46)
	v_fmac_f32_e32 v13, v51, v27
	v_add_f32_e32 v13, v21, v13
	s_waitcnt vmcnt(44) lgkmcnt(2)
	v_mul_f32_e32 v28, v58, v37
	v_fmac_f32_e32 v28, v50, v36
	s_waitcnt vmcnt(43)
	v_fmac_f32_e32 v28, v55, v38
	s_waitcnt vmcnt(42)
	v_fmac_f32_e32 v28, v56, v39
	v_add_f32_e32 v13, v13, v28
	s_waitcnt vmcnt(40) lgkmcnt(1)
	v_mul_f32_e32 v28, v62, v87
	v_fmac_f32_e32 v28, v59, v86
	s_waitcnt vmcnt(32)
	v_mul_f32_e32 v35, v78, v25
	s_waitcnt vmcnt(31)
	v_fmac_f32_e32 v35, v76, v24
	s_waitcnt vmcnt(30)
	v_fmac_f32_e32 v35, v74, v26
	s_waitcnt vmcnt(29)
	v_fmac_f32_e32 v35, v72, v27
	v_add_f32_e32 v35, v67, v35
	s_waitcnt vmcnt(27)
	v_mul_f32_e32 v41, v73, v37
	v_fmac_f32_e32 v28, v79, v88
	v_fmac_f32_e32 v28, v77, v89
	v_add_f32_e32 v13, v13, v28
	s_waitcnt lgkmcnt(0)
	v_mul_f32_e32 v28, v80, v91
	v_fmac_f32_e32 v28, v75, v90
	v_fmac_f32_e32 v41, v70, v36
	s_waitcnt vmcnt(26)
	v_fmac_f32_e32 v41, v71, v38
	s_waitcnt vmcnt(25)
	v_fmac_f32_e32 v41, v68, v39
	v_add_f32_e32 v35, v35, v41
	s_waitcnt vmcnt(23)
	v_mul_f32_e32 v41, v69, v87
	v_fmac_f32_e32 v41, v65, v86
	s_waitcnt vmcnt(22)
	v_fmac_f32_e32 v41, v66, v88
	s_waitcnt vmcnt(21)
	v_fmac_f32_e32 v41, v63, v89
	v_fmac_f32_e32 v28, v81, v92
	v_fmac_f32_e32 v28, v82, v93
	v_add_f32_e32 v13, v13, v28
	v_mul_f32_e64 v28, |v13|, s80
	v_exp_f32_e32 v28, v28
	v_add_f32_e32 v35, v35, v41
	s_waitcnt vmcnt(19)
	v_mul_f32_e32 v41, v64, v91
	v_fmac_f32_e32 v41, v60, v90
	v_add_f32_e32 v28, 1.0, v28
	v_cmp_gt_f32_e32 vcc, s84, v28
	s_waitcnt vmcnt(18)
	v_fmac_f32_e32 v41, v61, v92
	s_waitcnt vmcnt(2)
	v_mul_f32_e32 v25, v54, v25
	v_cndmask_b32_e64 v29, 0, 32, vcc
	v_ldexp_f32 v28, v28, v29
	v_log_f32_e32 v28, v28
	s_waitcnt vmcnt(1)
	v_fmac_f32_e32 v25, v53, v24
	v_fmac_f32_e32 v25, v43, v26
	v_fmac_f32_e32 v41, v57, v93
	v_fmac_f32_e32 v25, v30, v27
	v_add_f32_e32 v35, v35, v41
	v_add_f32_e32 v24, v12, v25
	v_mul_f32_e32 v25, v47, v37
	v_mul_f32_e32 v29, 0x3f317217, v28
	v_mul_f32_e64 v41, |v35|, s80
	v_fmac_f32_e32 v25, v34, v36
	v_fma_f32 v29, v28, s85, -v29
	v_exp_f32_e32 v41, v41
	v_fmac_f32_e32 v25, v16, v38
	v_fmac_f32_e32 v29, 0x3377d1cf, v28
	v_fmac_f32_e32 v25, v48, v39
	v_fmac_f32_e32 v29, 0x3f317217, v28
	v_cmp_lt_f32_e64 s[8:9], |v28|, s86
	v_add_f32_e32 v24, v24, v25
	v_mul_f32_e32 v25, v19, v87
	v_cndmask_b32_e64 v28, v28, v29, s[8:9]
	v_cndmask_b32_e32 v29, 0, v200, vcc
	v_fmac_f32_e32 v25, v17, v86
	v_sub_f32_e32 v28, v28, v29
	v_add_f32_e32 v29, 1.0, v41
	v_fmac_f32_e32 v25, v31, v88
	v_cmp_gt_f32_e32 vcc, s84, v29
	v_fmac_f32_e32 v25, v15, v89
	v_add_f32_e32 v24, v24, v25
	v_cndmask_b32_e64 v41, 0, 32, vcc
	v_mul_f32_e32 v25, v32, v91
	v_ldexp_f32 v29, v29, v41
	v_fmac_f32_e32 v25, v20, v90
	v_log_f32_e32 v29, v29
	v_fmac_f32_e32 v25, v14, v92
	s_waitcnt vmcnt(0)
	v_fmac_f32_e32 v25, v18, v93
	v_add_f32_e32 v24, v24, v25
	v_min_f32_e32 v13, 0, v13
	v_mul_f32_e64 v25, |v24|, s80
	v_sub_f32_e32 v13, v13, v28
	v_mul_f32_e32 v28, 0x3f317217, v29
	v_exp_f32_e32 v25, v25
	v_fma_f32 v28, v29, s85, -v28
	ds_read_b128 v[86:89], v84 offset:64
	v_fmac_f32_e32 v28, 0x3377d1cf, v29
	v_fmac_f32_e32 v28, 0x3f317217, v29
	v_cmp_lt_f32_e64 s[8:9], |v29|, s86
	v_cndmask_b32_e32 v27, 0, v200, vcc
	v_add_f32_e32 v25, 1.0, v25
	v_cndmask_b32_e64 v26, v29, v28, s[8:9]
	ds_read_b128 v[90:93], v84 offset:80
	ds_read_b128 v[94:97], v84 offset:96
	ds_read_b128 v[98:101], v84 offset:112
	v_fma_f32 v46, v13, s87, 0
	v_min_f32_e32 v13, 0, v35
	v_sub_f32_e32 v26, v26, v27
	v_cmp_gt_f32_e32 vcc, s84, v25
	v_sub_f32_e32 v13, v13, v26
	s_waitcnt lgkmcnt(3)
	v_mul_f32_e32 v26, v49, v87
	v_cndmask_b32_e64 v27, 0, 32, vcc
	v_ldexp_f32 v25, v25, v27
	v_fmac_f32_e32 v26, v33, v86
	s_waitcnt lgkmcnt(2)
	v_mul_f32_e32 v27, v58, v91
	v_fmac_f32_e32 v26, v52, v88
	v_fmac_f32_e32 v27, v50, v90
	v_fmac_f32_e32 v26, v51, v89
	v_fmac_f32_e32 v27, v55, v92
	v_add_f32_e32 v26, v21, v26
	v_fmac_f32_e32 v27, v56, v93
	v_add_f32_e32 v26, v26, v27
	s_waitcnt lgkmcnt(1)
	v_mul_f32_e32 v27, v62, v95
	v_fmac_f32_e32 v27, v59, v94
	v_fmac_f32_e32 v27, v79, v96
	v_fmac_f32_e32 v27, v77, v97
	v_add_f32_e32 v26, v26, v27
	s_waitcnt lgkmcnt(0)
	v_mul_f32_e32 v27, v80, v99
	v_log_f32_e32 v25, v25
	v_fmac_f32_e32 v27, v75, v98
	v_fmac_f32_e32 v27, v81, v100
	v_fmac_f32_e32 v27, v82, v101
	v_add_f32_e32 v27, v26, v27
	v_fma_f32 v37, v13, s87, 0
	v_min_f32_e32 v13, 0, v24
	v_mul_f32_e32 v24, 0x3f317217, v25
	v_mul_f32_e64 v26, |v27|, s80
	v_fma_f32 v24, v25, s85, -v24
	v_exp_f32_e32 v26, v26
	v_fmac_f32_e32 v24, 0x3377d1cf, v25
	v_fmac_f32_e32 v24, 0x3f317217, v25
	v_cmp_lt_f32_e64 s[8:9], |v25|, s86
	v_mul_f32_e32 v28, v73, v91
	v_fmac_f32_e32 v28, v70, v90
	v_cndmask_b32_e64 v24, v25, v24, s[8:9]
	v_cndmask_b32_e32 v25, 0, v200, vcc
	v_sub_f32_e32 v24, v24, v25
	v_add_f32_e32 v25, 1.0, v26
	v_cmp_gt_f32_e32 vcc, s84, v25
	v_sub_f32_e32 v13, v13, v24
	v_fmac_f32_e32 v28, v71, v92
	v_cndmask_b32_e64 v26, 0, 32, vcc
	v_ldexp_f32 v25, v25, v26
	v_fma_f32 v26, v13, s87, 0
	v_min_f32_e32 v13, 0, v27
	v_mul_f32_e32 v27, v78, v87
	v_fmac_f32_e32 v27, v76, v86
	v_fmac_f32_e32 v27, v74, v88
	v_fmac_f32_e32 v27, v72, v89
	v_add_f32_e32 v27, v67, v27
	v_fmac_f32_e32 v28, v68, v93
	v_add_f32_e32 v27, v27, v28
	v_mul_f32_e32 v28, v69, v95
	v_fmac_f32_e32 v28, v65, v94
	v_fmac_f32_e32 v28, v66, v96
	v_fmac_f32_e32 v28, v63, v97
	v_add_f32_e32 v27, v27, v28
	v_mul_f32_e32 v28, v64, v99
	v_log_f32_e32 v25, v25
	v_fmac_f32_e32 v28, v60, v98
	v_fmac_f32_e32 v28, v61, v100
	v_fmac_f32_e32 v28, v57, v101
	v_add_f32_e32 v27, v27, v28
	v_mul_f32_e32 v24, 0x3f317217, v25
	v_mul_f32_e64 v28, |v27|, s80
	v_fma_f32 v24, v25, s85, -v24
	v_exp_f32_e32 v28, v28
	v_fmac_f32_e32 v24, 0x3377d1cf, v25
	v_fmac_f32_e32 v24, 0x3f317217, v25
	v_cmp_lt_f32_e64 s[8:9], |v25|, s86
	s_nop 1
	v_cndmask_b32_e64 v24, v25, v24, s[8:9]
	v_cndmask_b32_e32 v25, 0, v200, vcc
	v_sub_f32_e32 v24, v24, v25
	v_add_f32_e32 v25, 1.0, v28
	v_cmp_gt_f32_e32 vcc, s84, v25
	v_sub_f32_e32 v13, v13, v24
	v_fmamk_f32 v42, v13, 0x3d800000, v46
	v_cndmask_b32_e64 v28, 0, 32, vcc
	v_min_f32_e32 v13, 0, v27
	v_mul_f32_e32 v27, v54, v87
	v_ldexp_f32 v25, v25, v28
	v_fmac_f32_e32 v27, v53, v86
	v_mul_f32_e32 v28, v47, v91
	v_fmac_f32_e32 v27, v43, v88
	v_fmac_f32_e32 v28, v34, v90
	v_fmac_f32_e32 v27, v30, v89
	v_fmac_f32_e32 v28, v16, v92
	v_add_f32_e32 v27, v12, v27
	v_fmac_f32_e32 v28, v48, v93
	v_add_f32_e32 v27, v27, v28
	v_mul_f32_e32 v28, v19, v95
	v_fmac_f32_e32 v28, v17, v94
	v_fmac_f32_e32 v28, v31, v96
	v_fmac_f32_e32 v28, v15, v97
	v_add_f32_e32 v27, v27, v28
	v_mul_f32_e32 v28, v32, v99
	v_log_f32_e32 v25, v25
	v_fmac_f32_e32 v28, v20, v98
	v_fmac_f32_e32 v28, v14, v100
	v_fmac_f32_e32 v28, v18, v101
	v_add_f32_e32 v27, v27, v28
	v_mul_f32_e32 v24, 0x3f317217, v25
	v_mul_f32_e64 v28, |v27|, s80
	v_fma_f32 v24, v25, s85, -v24
	v_exp_f32_e32 v28, v28
	v_fmac_f32_e32 v24, 0x3377d1cf, v25
	v_fmac_f32_e32 v24, 0x3f317217, v25
	v_cmp_lt_f32_e64 s[8:9], |v25|, s86
	ds_read_b128 v[86:89], v84 offset:128
	ds_read_b128 v[90:93], v84 offset:144
	ds_read_b128 v[94:97], v84 offset:160
	ds_read_b128 v[98:101], v84 offset:176
	v_cndmask_b32_e64 v24, v25, v24, s[8:9]
	v_cndmask_b32_e32 v25, 0, v200, vcc
	v_sub_f32_e32 v24, v24, v25
	v_add_f32_e32 v25, 1.0, v28
	v_cmp_gt_f32_e32 vcc, s84, v25
	s_waitcnt lgkmcnt(2)
	v_mul_f32_e32 v29, v58, v91
	v_fmac_f32_e32 v29, v50, v90
	v_cndmask_b32_e64 v28, 0, 32, vcc
	v_ldexp_f32 v25, v25, v28
	v_mul_f32_e32 v28, v49, v87
	v_fmac_f32_e32 v28, v33, v86
	v_fmac_f32_e32 v28, v52, v88
	v_fmac_f32_e32 v28, v51, v89
	v_fmac_f32_e32 v29, v55, v92
	v_add_f32_e32 v28, v21, v28
	v_fmac_f32_e32 v29, v56, v93
	v_add_f32_e32 v28, v28, v29
	s_waitcnt lgkmcnt(1)
	v_mul_f32_e32 v29, v62, v95
	v_fmac_f32_e32 v29, v59, v94
	v_fmac_f32_e32 v29, v79, v96
	v_fmac_f32_e32 v29, v77, v97
	v_add_f32_e32 v28, v28, v29
	s_waitcnt lgkmcnt(0)
	v_mul_f32_e32 v29, v80, v99
	v_log_f32_e32 v25, v25
	v_fmac_f32_e32 v29, v75, v98
	v_fmac_f32_e32 v29, v81, v100
	v_fmac_f32_e32 v29, v82, v101
	v_add_f32_e32 v28, v28, v29
	v_sub_f32_e32 v13, v13, v24
	v_min_f32_e32 v24, 0, v27
	v_mul_f32_e32 v27, 0x3f317217, v25
	v_mul_f32_e64 v29, |v28|, s80
	v_fma_f32 v27, v25, s85, -v27
	v_exp_f32_e32 v29, v29
	v_fmac_f32_e32 v27, 0x3377d1cf, v25
	v_fmac_f32_e32 v27, 0x3f317217, v25
	v_cmp_lt_f32_e64 s[8:9], |v25|, s86
	v_mul_f32_e32 v35, v73, v91
	v_fmac_f32_e32 v35, v70, v90
	v_cndmask_b32_e64 v25, v25, v27, s[8:9]
	v_cndmask_b32_e32 v27, 0, v200, vcc
	v_sub_f32_e32 v25, v25, v27
	v_add_f32_e32 v27, 1.0, v29
	v_cmp_gt_f32_e32 vcc, s84, v27
	v_fmac_f32_e32 v35, v71, v92
	v_fmac_f32_e32 v35, v68, v93
	v_cndmask_b32_e64 v29, 0, 32, vcc
	v_ldexp_f32 v27, v27, v29
	v_mul_f32_e32 v29, v78, v87
	v_fmac_f32_e32 v29, v76, v86
	v_fmac_f32_e32 v29, v74, v88
	v_fmac_f32_e32 v29, v72, v89
	v_add_f32_e32 v29, v67, v29
	v_add_f32_e32 v29, v29, v35
	v_mul_f32_e32 v35, v69, v95
	v_fmac_f32_e32 v35, v65, v94
	v_fmac_f32_e32 v35, v66, v96
	v_fmac_f32_e32 v35, v63, v97
	v_add_f32_e32 v29, v29, v35
	v_mul_f32_e32 v35, v64, v99
	v_log_f32_e32 v27, v27
	v_fmac_f32_e32 v35, v60, v98
	v_fmac_f32_e32 v35, v61, v100
	v_fmac_f32_e32 v35, v57, v101
	v_add_f32_e32 v29, v29, v35
	v_sub_f32_e32 v24, v24, v25
	v_min_f32_e32 v25, 0, v28
	v_mul_f32_e32 v28, 0x3f317217, v27
	v_mul_f32_e64 v35, |v29|, s80
	v_fma_f32 v28, v27, s85, -v28
	v_exp_f32_e32 v35, v35
	v_fmac_f32_e32 v28, 0x3377d1cf, v27
	v_fmac_f32_e32 v28, 0x3f317217, v27
	v_cmp_lt_f32_e64 s[8:9], |v27|, s86
	v_fmamk_f32 v13, v13, 0x3d800000, v37
	v_fmamk_f32 v24, v24, 0x3d800000, v26
	v_cndmask_b32_e64 v27, v27, v28, s[8:9]
	v_cndmask_b32_e32 v28, 0, v200, vcc
	v_sub_f32_e32 v27, v27, v28
	v_add_f32_e32 v28, 1.0, v35
	v_cmp_gt_f32_e32 vcc, s84, v28
	v_sub_f32_e32 v25, v25, v27
	v_fmamk_f32 v44, v25, 0x3d800000, v42
	v_cndmask_b32_e64 v35, 0, 32, vcc
	v_min_f32_e32 v25, 0, v29
	v_mul_f32_e32 v29, v54, v87
	v_ldexp_f32 v28, v28, v35
	v_fmac_f32_e32 v29, v53, v86
	v_mul_f32_e32 v35, v47, v91
	v_fmac_f32_e32 v29, v43, v88
	v_fmac_f32_e32 v35, v34, v90
	v_fmac_f32_e32 v29, v30, v89
	v_fmac_f32_e32 v35, v16, v92
	v_add_f32_e32 v29, v12, v29
	v_fmac_f32_e32 v35, v48, v93
	v_add_f32_e32 v29, v29, v35
	v_mul_f32_e32 v35, v19, v95
	v_fmac_f32_e32 v35, v17, v94
	v_fmac_f32_e32 v35, v31, v96
	v_fmac_f32_e32 v35, v15, v97
	v_add_f32_e32 v29, v29, v35
	v_mul_f32_e32 v35, v32, v99
	v_log_f32_e32 v28, v28
	v_fmac_f32_e32 v35, v20, v98
	v_fmac_f32_e32 v35, v14, v100
	v_fmac_f32_e32 v35, v18, v101
	v_add_f32_e32 v29, v29, v35
	v_mul_f32_e32 v27, 0x3f317217, v28
	v_mul_f32_e64 v35, |v29|, s80
	v_fma_f32 v27, v28, s85, -v27
	v_exp_f32_e32 v35, v35
	v_fmac_f32_e32 v27, 0x3377d1cf, v28
	v_fmac_f32_e32 v27, 0x3f317217, v28
	v_cmp_lt_f32_e64 s[8:9], |v28|, s86
	ds_read_b128 v[86:89], v84 offset:192
	ds_read_b128 v[90:93], v84 offset:208
	ds_read_b128 v[94:97], v84 offset:224
	ds_read_b128 v[98:101], v84 offset:240
	v_cndmask_b32_e64 v27, v28, v27, s[8:9]
	v_cndmask_b32_e32 v28, 0, v200, vcc
	v_sub_f32_e32 v27, v27, v28
	v_add_f32_e32 v28, 1.0, v35
	v_cmp_gt_f32_e32 vcc, s84, v28
	v_sub_f32_e32 v25, v25, v27
	s_waitcnt lgkmcnt(2)
	v_mul_f32_e32 v36, v58, v91
	v_cndmask_b32_e64 v35, 0, 32, vcc
	v_ldexp_f32 v28, v28, v35
	v_fmamk_f32 v35, v25, 0x3d800000, v13
	v_min_f32_e32 v25, 0, v29
	v_mul_f32_e32 v29, v49, v87
	v_fmac_f32_e32 v29, v33, v86
	v_fmac_f32_e32 v29, v52, v88
	v_fmac_f32_e32 v36, v50, v90
	v_fmac_f32_e32 v29, v51, v89
	v_fmac_f32_e32 v36, v55, v92
	v_add_f32_e32 v29, v21, v29
	v_fmac_f32_e32 v36, v56, v93
	v_add_f32_e32 v29, v29, v36
	s_waitcnt lgkmcnt(1)
	v_mul_f32_e32 v36, v62, v95
	v_fmac_f32_e32 v36, v59, v94
	v_fmac_f32_e32 v36, v79, v96
	v_fmac_f32_e32 v36, v77, v97
	v_add_f32_e32 v29, v29, v36
	s_waitcnt lgkmcnt(0)
	v_mul_f32_e32 v36, v80, v99
	v_log_f32_e32 v28, v28
	v_fmac_f32_e32 v36, v75, v98
	v_fmac_f32_e32 v36, v81, v100
	v_fmac_f32_e32 v36, v82, v101
	v_add_f32_e32 v29, v29, v36
	v_mul_f32_e32 v27, 0x3f317217, v28
	v_mul_f32_e64 v36, |v29|, s80
	v_fma_f32 v27, v28, s85, -v27
	v_exp_f32_e32 v36, v36
	v_fmac_f32_e32 v27, 0x3377d1cf, v28
	v_fmac_f32_e32 v27, 0x3f317217, v28
	v_cmp_lt_f32_e64 s[8:9], |v28|, s86
	v_mul_f32_e32 v38, v73, v91
	v_fmac_f32_e32 v38, v70, v90
	v_cndmask_b32_e64 v27, v28, v27, s[8:9]
	v_cndmask_b32_e32 v28, 0, v200, vcc
	v_sub_f32_e32 v27, v27, v28
	v_add_f32_e32 v28, 1.0, v36
	v_cmp_gt_f32_e32 vcc, s84, v28
	v_fmac_f32_e32 v38, v71, v92
	v_fmac_f32_e32 v38, v68, v93
	v_cndmask_b32_e64 v36, 0, 32, vcc
	v_ldexp_f32 v28, v28, v36
	v_mul_f32_e32 v36, v78, v87
	v_fmac_f32_e32 v36, v76, v86
	v_fmac_f32_e32 v36, v74, v88
	v_fmac_f32_e32 v36, v72, v89
	v_add_f32_e32 v36, v67, v36
	v_add_f32_e32 v36, v36, v38
	v_mul_f32_e32 v38, v69, v95
	v_fmac_f32_e32 v38, v65, v94
	v_fmac_f32_e32 v38, v66, v96
	v_fmac_f32_e32 v38, v63, v97
	v_add_f32_e32 v36, v36, v38
	v_mul_f32_e32 v38, v64, v99
	v_log_f32_e32 v28, v28
	v_fmac_f32_e32 v38, v60, v98
	v_fmac_f32_e32 v38, v61, v100
	v_fmac_f32_e32 v38, v57, v101
	v_add_f32_e32 v36, v36, v38
	v_sub_f32_e32 v25, v25, v27
	v_min_f32_e32 v27, 0, v29
	v_mul_f32_e32 v29, 0x3f317217, v28
	v_mul_f32_e64 v38, |v36|, s80
	v_fma_f32 v29, v28, s85, -v29
	v_exp_f32_e32 v38, v38
	v_fmac_f32_e32 v29, 0x3377d1cf, v28
	v_fmac_f32_e32 v29, 0x3f317217, v28
	v_cmp_lt_f32_e64 s[8:9], |v28|, s86
	v_fmamk_f32 v25, v25, 0x3d800000, v24
	s_nop 0
	v_cndmask_b32_e64 v28, v28, v29, s[8:9]
	v_cndmask_b32_e32 v29, 0, v200, vcc
	v_sub_f32_e32 v28, v28, v29
	v_add_f32_e32 v29, 1.0, v38
	v_cmp_gt_f32_e32 vcc, s84, v29
	v_sub_f32_e32 v27, v27, v28
	v_fmamk_f32 v45, v27, 0x3d800000, v44
	v_cndmask_b32_e64 v38, 0, 32, vcc
	v_min_f32_e32 v27, 0, v36
	v_mul_f32_e32 v36, v54, v87
	v_ldexp_f32 v29, v29, v38
	v_fmac_f32_e32 v36, v53, v86
	v_mul_f32_e32 v38, v47, v91
	v_fmac_f32_e32 v36, v43, v88
	v_fmac_f32_e32 v38, v34, v90
	v_fmac_f32_e32 v36, v30, v89
	v_fmac_f32_e32 v38, v16, v92
	v_add_f32_e32 v36, v12, v36
	v_fmac_f32_e32 v38, v48, v93
	v_add_f32_e32 v36, v36, v38
	v_mul_f32_e32 v38, v19, v95
	v_fmac_f32_e32 v38, v17, v94
	v_fmac_f32_e32 v38, v31, v96
	v_fmac_f32_e32 v38, v15, v97
	v_add_f32_e32 v36, v36, v38
	v_mul_f32_e32 v38, v32, v99
	v_log_f32_e32 v29, v29
	v_fmac_f32_e32 v38, v20, v98
	v_fmac_f32_e32 v38, v14, v100
	v_fmac_f32_e32 v38, v18, v101
	v_add_f32_e32 v38, v36, v38
	v_mul_f32_e32 v28, 0x3f317217, v29
	v_mul_f32_e64 v36, |v38|, s80
	v_fma_f32 v28, v29, s85, -v28
	v_exp_f32_e32 v36, v36
	v_fmac_f32_e32 v28, 0x3377d1cf, v29
	v_fmac_f32_e32 v28, 0x3f317217, v29
	v_cmp_lt_f32_e64 s[8:9], |v29|, s86
	ds_read_b128 v[86:89], v84 offset:256
	ds_read_b128 v[90:93], v84 offset:272
	ds_read_b128 v[94:97], v84 offset:288
	ds_read_b128 v[98:101], v84 offset:304
	v_cndmask_b32_e64 v28, v29, v28, s[8:9]
	v_cndmask_b32_e32 v29, 0, v200, vcc
	v_sub_f32_e32 v28, v28, v29
	v_add_f32_e32 v29, 1.0, v36
	v_cmp_gt_f32_e32 vcc, s84, v29
	v_sub_f32_e32 v27, v27, v28
	s_waitcnt lgkmcnt(2)
	v_mul_f32_e32 v39, v58, v91
	v_cndmask_b32_e64 v36, 0, 32, vcc
	v_ldexp_f32 v29, v29, v36
	v_fmamk_f32 v36, v27, 0x3d800000, v35
	v_min_f32_e32 v27, 0, v38
	v_mul_f32_e32 v38, v49, v87
	v_fmac_f32_e32 v38, v33, v86
	v_fmac_f32_e32 v38, v52, v88
	v_fmac_f32_e32 v39, v50, v90
	v_fmac_f32_e32 v38, v51, v89
	v_fmac_f32_e32 v39, v55, v92
	v_add_f32_e32 v38, v21, v38
	v_fmac_f32_e32 v39, v56, v93
	v_add_f32_e32 v38, v38, v39
	s_waitcnt lgkmcnt(1)
	v_mul_f32_e32 v39, v62, v95
	v_fmac_f32_e32 v39, v59, v94
	v_fmac_f32_e32 v39, v79, v96
	v_fmac_f32_e32 v39, v77, v97
	v_add_f32_e32 v38, v38, v39
	s_waitcnt lgkmcnt(0)
	v_mul_f32_e32 v39, v80, v99
	v_log_f32_e32 v29, v29
	v_fmac_f32_e32 v39, v75, v98
	v_fmac_f32_e32 v39, v81, v100
	v_fmac_f32_e32 v39, v82, v101
	v_add_f32_e32 v38, v38, v39
	v_mul_f32_e32 v28, 0x3f317217, v29
	v_mul_f32_e64 v39, |v38|, s80
	v_fma_f32 v28, v29, s85, -v28
	v_exp_f32_e32 v39, v39
	v_fmac_f32_e32 v28, 0x3377d1cf, v29
	v_fmac_f32_e32 v28, 0x3f317217, v29
	v_cmp_lt_f32_e64 s[8:9], |v29|, s86
	v_mul_f32_e32 v41, v73, v91
	v_fmac_f32_e32 v41, v70, v90
	v_cndmask_b32_e64 v28, v29, v28, s[8:9]
	v_cndmask_b32_e32 v29, 0, v200, vcc
	v_sub_f32_e32 v28, v28, v29
	v_add_f32_e32 v29, 1.0, v39
	v_cmp_gt_f32_e32 vcc, s84, v29
	v_fmac_f32_e32 v41, v71, v92
	v_fmac_f32_e32 v41, v68, v93
	v_cndmask_b32_e64 v39, 0, 32, vcc
	v_ldexp_f32 v29, v29, v39
	v_mul_f32_e32 v39, v78, v87
	v_fmac_f32_e32 v39, v76, v86
	v_fmac_f32_e32 v39, v74, v88
	v_fmac_f32_e32 v39, v72, v89
	v_add_f32_e32 v39, v67, v39
	v_add_f32_e32 v39, v39, v41
	v_mul_f32_e32 v41, v69, v95
	v_fmac_f32_e32 v41, v65, v94
	v_fmac_f32_e32 v41, v66, v96
	v_fmac_f32_e32 v41, v63, v97
	v_add_f32_e32 v39, v39, v41
	v_mul_f32_e32 v41, v64, v99
	v_log_f32_e32 v29, v29
	v_fmac_f32_e32 v41, v60, v98
	v_fmac_f32_e32 v41, v61, v100
	v_fmac_f32_e32 v41, v57, v101
	v_add_f32_e32 v39, v39, v41
	v_sub_f32_e32 v27, v27, v28
	v_min_f32_e32 v28, 0, v38
	v_mul_f32_e32 v38, 0x3f317217, v29
	v_mul_f32_e64 v41, |v39|, s80
	v_fma_f32 v38, v29, s85, -v38
	v_exp_f32_e32 v41, v41
	v_fmac_f32_e32 v38, 0x3377d1cf, v29
	v_fmac_f32_e32 v38, 0x3f317217, v29
	v_cmp_lt_f32_e64 s[8:9], |v29|, s86
	v_fmamk_f32 v27, v27, 0x3d800000, v25
	s_nop 0
	v_cndmask_b32_e64 v29, v29, v38, s[8:9]
	v_cndmask_b32_e32 v38, 0, v200, vcc
	v_sub_f32_e32 v29, v29, v38
	v_add_f32_e32 v38, 1.0, v41
	v_cmp_gt_f32_e32 vcc, s84, v38
	v_sub_f32_e32 v28, v28, v29
	v_fmamk_f32 v83, v28, 0x3d800000, v45
	v_cndmask_b32_e64 v41, 0, 32, vcc
	v_min_f32_e32 v28, 0, v39
	v_mul_f32_e32 v39, v54, v87
	v_ldexp_f32 v38, v38, v41
	v_fmac_f32_e32 v39, v53, v86
	v_mul_f32_e32 v41, v47, v91
	v_fmac_f32_e32 v39, v43, v88
	v_fmac_f32_e32 v41, v34, v90
	v_fmac_f32_e32 v39, v30, v89
	v_fmac_f32_e32 v41, v16, v92
	v_add_f32_e32 v39, v12, v39
	v_fmac_f32_e32 v41, v48, v93
	v_add_f32_e32 v39, v39, v41
	v_mul_f32_e32 v41, v19, v95
	v_fmac_f32_e32 v41, v17, v94
	v_fmac_f32_e32 v41, v31, v96
	v_fmac_f32_e32 v41, v15, v97
	v_add_f32_e32 v39, v39, v41
	v_mul_f32_e32 v41, v32, v99
	v_log_f32_e32 v38, v38
	v_fmac_f32_e32 v41, v20, v98
	v_fmac_f32_e32 v41, v14, v100
	v_fmac_f32_e32 v41, v18, v101
	v_add_f32_e32 v39, v39, v41
	v_mul_f32_e32 v29, 0x3f317217, v38
	v_mul_f32_e64 v41, |v39|, s80
	v_fma_f32 v29, v38, s85, -v29
	v_exp_f32_e32 v41, v41
	v_fmac_f32_e32 v29, 0x3377d1cf, v38
	v_fmac_f32_e32 v29, 0x3f317217, v38
	v_cmp_lt_f32_e64 s[8:9], |v38|, s86
	ds_read_b128 v[86:89], v84 offset:320
	ds_read_b128 v[90:93], v84 offset:336
	ds_read_b128 v[94:97], v84 offset:352
	ds_read_b128 v[98:101], v84 offset:368
	v_cndmask_b32_e64 v29, v38, v29, s[8:9]
	v_cndmask_b32_e32 v38, 0, v200, vcc
	v_sub_f32_e32 v29, v29, v38
	v_add_f32_e32 v38, 1.0, v41
	v_cmp_gt_f32_e32 vcc, s84, v38
	v_sub_f32_e32 v28, v28, v29
	s_waitcnt lgkmcnt(2)
	v_mul_f32_e32 v85, v58, v91
	v_cndmask_b32_e64 v41, 0, 32, vcc
	v_ldexp_f32 v38, v38, v41
	v_log_f32_e32 v41, v38
	v_fmamk_f32 v38, v28, 0x3d800000, v36
	v_min_f32_e32 v28, 0, v39
	v_mul_f32_e32 v39, v49, v87
	v_fmac_f32_e32 v39, v33, v86
	v_fmac_f32_e32 v39, v52, v88
	v_fmac_f32_e32 v85, v50, v90
	v_fmac_f32_e32 v39, v51, v89
	v_fmac_f32_e32 v85, v55, v92
	v_add_f32_e32 v39, v21, v39
	v_fmac_f32_e32 v85, v56, v93
	v_add_f32_e32 v39, v39, v85
	s_waitcnt lgkmcnt(1)
	v_mul_f32_e32 v85, v62, v95
	v_fmac_f32_e32 v85, v59, v94
	v_fmac_f32_e32 v85, v79, v96
	v_fmac_f32_e32 v85, v77, v97
	v_add_f32_e32 v39, v39, v85
	s_waitcnt lgkmcnt(0)
	v_mul_f32_e32 v85, v80, v99
	v_fmac_f32_e32 v85, v75, v98
	v_fmac_f32_e32 v85, v81, v100
	v_fmac_f32_e32 v85, v82, v101
	v_add_f32_e32 v39, v39, v85
	v_mul_f32_e32 v29, 0x3f317217, v41
	v_mul_f32_e64 v85, |v39|, s80
	v_fma_f32 v29, v41, s85, -v29
	v_exp_f32_e32 v85, v85
	v_fmac_f32_e32 v29, 0x3377d1cf, v41
	v_fmac_f32_e32 v29, 0x3f317217, v41
	v_cmp_lt_f32_e64 s[8:9], |v41|, s86
	v_mul_f32_e32 v102, v73, v91
	v_fmac_f32_e32 v102, v70, v90
	v_cndmask_b32_e64 v29, v41, v29, s[8:9]
	v_cndmask_b32_e32 v41, 0, v200, vcc
	v_sub_f32_e32 v29, v29, v41
	v_add_f32_e32 v41, 1.0, v85
	v_cmp_gt_f32_e32 vcc, s84, v41
	v_fmac_f32_e32 v102, v71, v92
	v_fmac_f32_e32 v102, v68, v93
	v_cndmask_b32_e64 v85, 0, 32, vcc
	v_ldexp_f32 v41, v41, v85
	v_mul_f32_e32 v85, v78, v87
	v_fmac_f32_e32 v85, v76, v86
	v_fmac_f32_e32 v85, v74, v88
	v_fmac_f32_e32 v85, v72, v89
	v_add_f32_e32 v85, v67, v85
	v_add_f32_e32 v85, v85, v102
	v_mul_f32_e32 v102, v69, v95
	v_fmac_f32_e32 v102, v65, v94
	v_fmac_f32_e32 v102, v66, v96
	v_fmac_f32_e32 v102, v63, v97
	v_add_f32_e32 v85, v85, v102
	v_mul_f32_e32 v102, v64, v99
	v_log_f32_e32 v41, v41
	v_fmac_f32_e32 v102, v60, v98
	v_mul_f32_e32 v87, v54, v87
	v_fmac_f32_e32 v102, v61, v100
	v_fmac_f32_e32 v87, v53, v86
	v_fmac_f32_e32 v102, v57, v101
	v_fmac_f32_e32 v87, v43, v88
	v_add_f32_e32 v102, v85, v102
	v_fmac_f32_e32 v87, v30, v89
	v_sub_f32_e32 v28, v28, v29
	v_min_f32_e32 v29, 0, v39
	v_mul_f32_e32 v39, 0x3f317217, v41
	v_mul_f32_e64 v85, |v102|, s80
	v_add_f32_e32 v86, v12, v87
	v_mul_f32_e32 v87, v47, v91
	v_fma_f32 v39, v41, s85, -v39
	v_exp_f32_e32 v85, v85
	v_fmac_f32_e32 v87, v34, v90
	v_fmac_f32_e32 v39, 0x3377d1cf, v41
	v_fmac_f32_e32 v87, v16, v92
	v_fmac_f32_e32 v39, 0x3f317217, v41
	v_cmp_lt_f32_e64 s[8:9], |v41|, s86
	v_fmac_f32_e32 v87, v48, v93
	v_add_f32_e32 v86, v86, v87
	v_cndmask_b32_e64 v39, v41, v39, s[8:9]
	v_cndmask_b32_e32 v41, 0, v200, vcc
	v_mul_f32_e32 v87, v19, v95
	v_sub_f32_e32 v39, v39, v41
	v_add_f32_e32 v41, 1.0, v85
	v_fmac_f32_e32 v87, v17, v94
	v_cmp_gt_f32_e32 vcc, s84, v41
	v_fmac_f32_e32 v87, v31, v96
	v_fmac_f32_e32 v87, v15, v97
	v_cndmask_b32_e64 v85, 0, 32, vcc
	v_ldexp_f32 v41, v41, v85
	v_add_f32_e32 v86, v86, v87
	v_mul_f32_e32 v87, v32, v99
	v_log_f32_e32 v41, v41
	v_fmac_f32_e32 v87, v20, v98
	v_fmac_f32_e32 v87, v14, v100
	v_fmac_f32_e32 v87, v18, v101
	v_add_f32_e32 v86, v86, v87
	v_sub_f32_e32 v29, v29, v39
	v_mul_f32_e32 v39, 0x3f317217, v41
	v_mul_f32_e64 v87, |v86|, s80
	v_fma_f32 v39, v41, s85, -v39
	v_exp_f32_e32 v87, v87
	v_fmac_f32_e32 v39, 0x3377d1cf, v41
	v_fmac_f32_e32 v39, 0x3f317217, v41
	v_cmp_lt_f32_e64 s[8:9], |v41|, s86
	ds_read_b128 v[88:91], v84 offset:384
	v_fmamk_f32 v85, v29, 0x3d800000, v83
	v_cndmask_b32_e64 v39, v41, v39, s[8:9]
	v_cndmask_b32_e32 v41, 0, v200, vcc
	v_sub_f32_e32 v39, v39, v41
	v_add_f32_e32 v41, 1.0, v87
	v_min_f32_e32 v29, 0, v102
	v_cmp_gt_f32_e32 vcc, s84, v41
	ds_read_b128 v[92:95], v84 offset:400
	ds_read_b128 v[96:99], v84 offset:416
	ds_read_b128 v[100:103], v84 offset:432
	v_cndmask_b32_e64 v87, 0, 32, vcc
	v_ldexp_f32 v41, v41, v87
	s_waitcnt lgkmcnt(3)
	v_mul_f32_e32 v87, v49, v89
	v_fmac_f32_e32 v87, v33, v88
	s_waitcnt lgkmcnt(2)
	v_mul_f32_e32 v104, v58, v93
	v_fmac_f32_e32 v87, v52, v90
	v_fmac_f32_e32 v104, v50, v92
	v_fmac_f32_e32 v87, v51, v91
	v_fmac_f32_e32 v104, v55, v94
	v_add_f32_e32 v87, v21, v87
	v_fmac_f32_e32 v104, v56, v95
	v_add_f32_e32 v87, v87, v104
	s_waitcnt lgkmcnt(1)
	v_mul_f32_e32 v104, v62, v97
	v_fmac_f32_e32 v104, v59, v96
	v_fmac_f32_e32 v104, v79, v98
	v_fmac_f32_e32 v104, v77, v99
	v_add_f32_e32 v87, v87, v104
	s_waitcnt lgkmcnt(0)
	v_mul_f32_e32 v104, v80, v101
	v_log_f32_e32 v41, v41
	v_fmac_f32_e32 v104, v75, v100
	v_fmac_f32_e32 v104, v81, v102
	v_fmac_f32_e32 v104, v82, v103
	v_sub_f32_e32 v29, v29, v39
	v_add_f32_e32 v87, v87, v104
	v_fmamk_f32 v39, v29, 0x3d800000, v38
	v_min_f32_e32 v29, 0, v86
	v_mul_f32_e32 v86, 0x3f317217, v41
	v_mul_f32_e64 v104, |v87|, s80
	v_fma_f32 v86, v41, s85, -v86
	v_exp_f32_e32 v104, v104
	v_fmac_f32_e32 v86, 0x3377d1cf, v41
	v_fmac_f32_e32 v86, 0x3f317217, v41
	v_cmp_lt_f32_e64 s[8:9], |v41|, s86
	v_mul_f32_e32 v105, v73, v93
	v_fmac_f32_e32 v105, v70, v92
	v_cndmask_b32_e64 v41, v41, v86, s[8:9]
	v_cndmask_b32_e32 v86, 0, v200, vcc
	v_sub_f32_e32 v41, v41, v86
	v_add_f32_e32 v86, 1.0, v104
	v_cmp_gt_f32_e32 vcc, s84, v86
	v_fmac_f32_e32 v105, v71, v94
	v_fmac_f32_e32 v105, v68, v95
	v_cndmask_b32_e64 v104, 0, 32, vcc
	v_ldexp_f32 v86, v86, v104
	v_mul_f32_e32 v104, v78, v89
	v_fmac_f32_e32 v104, v76, v88
	v_fmac_f32_e32 v104, v74, v90
	v_fmac_f32_e32 v104, v72, v91
	v_add_f32_e32 v104, v67, v104
	v_add_f32_e32 v104, v104, v105
	v_mul_f32_e32 v105, v69, v97
	v_fmac_f32_e32 v105, v65, v96
	v_fmac_f32_e32 v105, v66, v98
	v_fmac_f32_e32 v105, v63, v99
	v_mul_f32_e32 v89, v54, v89
	v_add_f32_e32 v104, v104, v105
	v_mul_f32_e32 v105, v64, v101
	v_fmac_f32_e32 v89, v53, v88
	v_log_f32_e32 v86, v86
	v_fmac_f32_e32 v105, v60, v100
	v_fmac_f32_e32 v89, v43, v90
	v_fmac_f32_e32 v105, v61, v102
	v_fmac_f32_e32 v89, v30, v91
	v_fmac_f32_e32 v105, v57, v103
	v_add_f32_e32 v88, v12, v89
	v_mul_f32_e32 v89, v47, v93
	v_add_f32_e32 v104, v104, v105
	v_fmac_f32_e32 v89, v34, v92
	v_sub_f32_e32 v29, v29, v41
	v_min_f32_e32 v41, 0, v87
	v_mul_f32_e32 v87, 0x3f317217, v86
	v_mul_f32_e64 v105, |v104|, s80
	v_fmac_f32_e32 v89, v16, v94
	v_fma_f32 v87, v86, s85, -v87
	v_exp_f32_e32 v105, v105
	v_fmac_f32_e32 v89, v48, v95
	v_fmac_f32_e32 v87, 0x3377d1cf, v86
	v_add_f32_e32 v88, v88, v89
	v_mul_f32_e32 v89, v19, v97
	v_fmac_f32_e32 v87, 0x3f317217, v86
	v_cmp_lt_f32_e64 s[8:9], |v86|, s86
	v_fmac_f32_e32 v89, v17, v96
	v_fmac_f32_e32 v89, v31, v98
	v_cndmask_b32_e64 v86, v86, v87, s[8:9]
	v_cndmask_b32_e32 v87, 0, v200, vcc
	v_sub_f32_e32 v86, v86, v87
	v_add_f32_e32 v87, 1.0, v105
	v_fmac_f32_e32 v89, v15, v99
	v_cmp_gt_f32_e32 vcc, s84, v87
	v_add_f32_e32 v88, v88, v89
	v_mul_f32_e32 v89, v32, v101
	v_cndmask_b32_e64 v105, 0, 32, vcc
	v_fmac_f32_e32 v89, v20, v100
	v_ldexp_f32 v87, v87, v105
	v_fmac_f32_e32 v89, v14, v102
	v_log_f32_e32 v87, v87
	v_fmac_f32_e32 v89, v18, v103
	v_add_f32_e32 v88, v88, v89
	v_mul_f32_e64 v89, |v88|, s80
	v_sub_f32_e32 v41, v41, v86
	v_exp_f32_e32 v89, v89
	v_fmamk_f32 v86, v41, 0x3d800000, v85
	v_min_f32_e32 v41, 0, v104
	v_mul_f32_e32 v104, 0x3f317217, v87
	v_fma_f32 v104, v87, s85, -v104
	v_fmac_f32_e32 v104, 0x3377d1cf, v87
	v_fmac_f32_e32 v104, 0x3f317217, v87
	v_cmp_lt_f32_e64 s[8:9], |v87|, s86
	v_add_f32_e32 v89, 1.0, v89
	v_cndmask_b32_e32 v90, 0, v200, vcc
	v_cndmask_b32_e64 v87, v87, v104, s[8:9]
	v_cmp_gt_f32_e32 vcc, s84, v89
	v_sub_f32_e32 v87, v87, v90
	v_sub_f32_e32 v41, v41, v87
	v_cndmask_b32_e64 v90, 0, 32, vcc
	v_ldexp_f32 v89, v89, v90
	v_log_f32_e32 v104, v89
	v_min_f32_e32 v87, 0, v88
	v_fmamk_f32 v41, v41, 0x3d800000, v39
	v_fmamk_f32 v28, v28, 0x3d800000, v27
	v_mul_f32_e32 v88, 0x3f317217, v104
	v_fma_f32 v105, v104, s85, -v88
	ds_read_b128 v[88:91], v84 offset:448
	ds_read_b128 v[92:95], v84 offset:464
	ds_read_b128 v[96:99], v84 offset:480
	ds_read_b128 v[100:103], v84 offset:496
	v_fmac_f32_e32 v105, 0x3377d1cf, v104
	v_fmac_f32_e32 v105, 0x3f317217, v104
	v_cmp_lt_f32_e64 s[8:9], |v104|, s86
	s_waitcnt lgkmcnt(3)
	v_mul_f32_e32 v49, v49, v89
	v_fmac_f32_e32 v49, v33, v88
	s_waitcnt lgkmcnt(2)
	v_mul_f32_e32 v33, v58, v93
	v_fmac_f32_e32 v49, v52, v90
	v_fmac_f32_e32 v33, v50, v92
	v_fmac_f32_e32 v49, v51, v91
	v_fmac_f32_e32 v33, v55, v94
	v_add_f32_e32 v21, v21, v49
	v_fmac_f32_e32 v33, v56, v95
	v_add_f32_e32 v21, v21, v33
	s_waitcnt lgkmcnt(1)
	v_mul_f32_e32 v33, v62, v97
	v_fmac_f32_e32 v33, v59, v96
	v_fmac_f32_e32 v33, v79, v98
	v_fmac_f32_e32 v33, v77, v99
	v_add_f32_e32 v21, v21, v33
	s_waitcnt lgkmcnt(0)
	v_mul_f32_e32 v33, v80, v101
	v_fmac_f32_e32 v33, v75, v100
	v_fmac_f32_e32 v33, v81, v102
	v_fmac_f32_e32 v33, v82, v103
	v_add_f32_e32 v21, v21, v33
	v_mul_f32_e32 v51, v78, v89
	v_mul_f32_e64 v33, |v21|, s80
	v_fmac_f32_e32 v51, v76, v88
	v_mul_f32_e32 v52, v73, v93
	v_exp_f32_e32 v33, v33
	v_fmac_f32_e32 v51, v74, v90
	v_fmac_f32_e32 v52, v70, v92
	v_fmac_f32_e32 v51, v72, v91
	v_fmac_f32_e32 v52, v71, v94
	v_add_f32_e32 v51, v67, v51
	v_fmac_f32_e32 v52, v68, v95
	v_add_f32_e32 v51, v51, v52
	v_mul_f32_e32 v52, v69, v97
	v_add_f32_e32 v33, 1.0, v33
	v_fmac_f32_e32 v52, v65, v96
	v_cndmask_b32_e64 v49, v104, v105, s[8:9]
	v_cndmask_b32_e32 v50, 0, v200, vcc
	v_cmp_gt_f32_e32 vcc, s84, v33
	v_fmac_f32_e32 v52, v66, v98
	v_sub_f32_e32 v49, v49, v50
	v_cndmask_b32_e64 v50, 0, 32, vcc
	v_fmac_f32_e32 v52, v63, v99
	v_ldexp_f32 v33, v33, v50
	v_add_f32_e32 v51, v51, v52
	v_mul_f32_e32 v52, v64, v101
	v_log_f32_e32 v50, v33
	v_fmac_f32_e32 v52, v60, v100
	v_fmac_f32_e32 v52, v61, v102
	v_fmac_f32_e32 v52, v57, v103
	v_add_f32_e32 v51, v51, v52
	v_sub_f32_e32 v33, v87, v49
	v_mul_f32_e32 v49, 0x3f317217, v50
	v_mul_f32_e64 v52, |v51|, s80
	v_fma_f32 v49, v50, s85, -v49
	v_exp_f32_e32 v52, v52
	v_fmac_f32_e32 v49, 0x3377d1cf, v50
	v_fmac_f32_e32 v49, 0x3f317217, v50
	v_cmp_lt_f32_e64 s[8:9], |v50|, s86
	v_min_f32_e32 v21, 0, v21
	v_fmamk_f32 v29, v29, 0x3d800000, v28
	v_cndmask_b32_e64 v49, v50, v49, s[8:9]
	v_cndmask_b32_e32 v50, 0, v200, vcc
	v_sub_f32_e32 v49, v49, v50
	v_add_f32_e32 v50, 1.0, v52
	v_cmp_gt_f32_e32 vcc, s84, v50
	v_sub_f32_e32 v21, v21, v49
	v_fmamk_f32 v49, v21, 0x3d800000, v86
	v_cndmask_b32_e64 v52, 0, 32, vcc
	v_ldexp_f32 v50, v50, v52
	v_mul_f32_e32 v52, v54, v89
	v_fmac_f32_e32 v52, v53, v88
	v_fmac_f32_e32 v52, v43, v90
	v_fmac_f32_e32 v52, v30, v91
	v_mul_f32_e32 v30, v47, v93
	v_fmac_f32_e32 v30, v34, v92
	v_fmac_f32_e32 v30, v16, v94
	v_mul_f32_e32 v16, v19, v97
	v_fmac_f32_e32 v16, v17, v96
	v_fmac_f32_e32 v16, v31, v98
	v_fmac_f32_e32 v16, v15, v99
	v_mul_f32_e32 v15, v32, v101
	v_add_f32_e32 v12, v12, v52
	v_fmac_f32_e32 v30, v48, v95
	v_fmac_f32_e32 v15, v20, v100
	v_add_f32_e32 v12, v12, v30
	v_fmac_f32_e32 v15, v14, v102
	v_log_f32_e32 v50, v50
	v_add_f32_e32 v12, v12, v16
	v_fmac_f32_e32 v15, v18, v103
	v_add_f32_e32 v12, v12, v15
	v_mul_f32_e64 v14, |v12|, s80
	v_exp_f32_e32 v14, v14
	v_min_f32_e32 v21, 0, v51
	v_mul_f32_e32 v51, 0x3f317217, v50
	v_fma_f32 v51, v50, s85, -v51
	v_fmac_f32_e32 v51, 0x3377d1cf, v50
	v_fmac_f32_e32 v51, 0x3f317217, v50
	v_cmp_lt_f32_e64 s[8:9], |v50|, s86
	v_add_f32_e32 v14, 1.0, v14
	v_cndmask_b32_e32 v16, 0, v200, vcc
	v_cndmask_b32_e64 v15, v50, v51, s[8:9]
	v_cmp_gt_f32_e32 vcc, s84, v14
	v_sub_f32_e32 v15, v15, v16
	v_sub_f32_e32 v15, v21, v15
	v_cndmask_b32_e64 v16, 0, 32, vcc
	v_ldexp_f32 v14, v14, v16
	v_log_f32_e32 v14, v14
	v_fmamk_f32 v43, v15, 0x3d800000, v41
	v_min_f32_e32 v12, 0, v12
	v_fmamk_f32 v33, v33, 0x3d800000, v29
	v_mul_f32_e32 v15, 0x3f317217, v14
	v_fma_f32 v15, v14, s85, -v15
	v_fmac_f32_e32 v15, 0x3377d1cf, v14
	v_fmac_f32_e32 v15, 0x3f317217, v14
	v_cmp_lt_f32_e64 s[8:9], |v14|, s86
	s_nop 1
	v_cndmask_b32_e64 v14, v14, v15, s[8:9]
	v_cndmask_b32_e32 v15, 0, v200, vcc
	v_sub_f32_e32 v14, v14, v15
	v_sub_f32_e32 v12, v12, v14
	v_fmamk_f32 v34, v12, 0x3d800000, v33
	v_add_u32_e32 v12, 0, v180
	s_movk_i32 s8, 0x300
	v_mad_u64_u32 v[14:15], s[8:9], v40, s8, v[12:13]
	ds_write2st64_b32 v14, v49, v43 offset0:20 offset1:21
	ds_write_b32 v14, v34 offset:5632
	s_waitcnt lgkmcnt(0)
	s_barrier
	ds_read2st64_b32 v[20:21], v12 offset0:20 offset1:23
	ds_read2st64_b32 v[18:19], v12 offset0:26 offset1:29
	ds_read2st64_b32 v[16:17], v12 offset0:32 offset1:35
	ds_read2st64_b32 v[14:15], v12 offset0:38 offset1:41
	v_cmp_gt_u32_e32 vcc, 64, v22
	s_waitcnt lgkmcnt(3)
	v_add_f32_e32 v47, 0, v20
	v_add_f32_e32 v20, v47, v21
	s_waitcnt lgkmcnt(2)
	v_add_f32_e32 v20, v20, v18
	v_add_f32_e32 v20, v20, v19
	s_waitcnt lgkmcnt(1)
	v_add_f32_e32 v20, v20, v16
	v_add_f32_e32 v20, v20, v17
	s_waitcnt lgkmcnt(0)
	v_add_f32_e32 v20, v20, v14
	v_add_f32_e32 v20, v20, v15
	s_and_saveexec_b64 s[8:9], vcc
	s_cbranch_execz .LBB0_476
	v_mul_f32_e32 v30, 0x3fb8aa3b, v20
	v_exp_f32_e32 v30, v30
	global_store_dword v180, v30, s[52:53] sc1
.LBB0_476:
	s_or_b64 exec, exec, s[8:9]
	v_lshlrev_b32_e32 v30, 3, v40
	v_and_b32_e32 v30, 8, v30
	v_cmp_eq_u32_e64 s[8:9], 0, v30
	v_cmp_lt_i32_e64 s[10:11], 1, v40
	v_cmp_lt_i32_e64 s[12:13], 2, v40
	v_cndmask_b32_e64 v48, 12, 8, s[8:9]
	v_cmp_lt_i32_e64 s[8:9], 0, v40
	v_cmp_lt_i32_e64 s[14:15], 3, v40
	v_cmp_lt_i32_e64 s[16:17], 4, v40
	v_cndmask_b32_e64 v47, 0, v47, s[8:9]
	v_add_f32_e32 v21, v21, v47
	v_cndmask_b32_e64 v21, v47, v21, s[10:11]
	v_add_f32_e32 v18, v18, v21
	v_cndmask_b32_e64 v18, v21, v18, s[12:13]
	v_add_f32_e32 v19, v19, v18
	v_cndmask_b32_e64 v18, v18, v19, s[14:15]
	v_add_f32_e32 v16, v16, v18
	v_cndmask_b32_e64 v16, v18, v16, s[16:17]
	v_add_f32_e32 v17, v17, v16
	v_cmp_lt_i32_e64 s[18:19], 5, v40
	v_cmp_lt_i32_e64 s[20:21], 6, v40
	v_cmp_lt_i32_e64 s[22:23], 7, v40
	v_cndmask_b32_e64 v16, v16, v17, s[18:19]
	v_add_f32_e32 v14, v14, v16
	v_cndmask_b32_e64 v14, v16, v14, s[20:21]
	v_add_f32_e32 v15, v15, v14
	v_cndmask_b32_e64 v19, v14, v15, s[22:23]
	v_lshlrev_b32_e32 v14, 1, v23
	s_movk_i32 s24, 0xc80
	v_sub_u32_e32 v14, v12, v14
	v_add_f32_e32 v15, v46, v19
	v_mul_lo_u32 v40, v40, s24
	v_add_u32_e32 v18, v14, v40
	v_mul_f32_e32 v14, 0x3fb8aa3b, v15
	v_ashrrev_i32_e32 v31, 3, v22
	v_exp_f32_e32 v14, v14
	v_and_b32_e32 v32, -16, v31
	v_lshlrev_b32_e32 v31, 1, v32
	v_or_b32_e32 v32, v48, v32
	ds_read_u16 v16, v18 offset:12288
	ds_read_u16 v17, v18 offset:12688
	ds_read_u16 v21, v18 offset:13088
	ds_read_u16 v46, v18 offset:13488
	ds_read_u16 v47, v18 offset:13888
	ds_read_u16 v48, v18 offset:14288
	ds_read_u16 v50, v18 offset:14688
	ds_read_u16 v51, v18 offset:15088
	s_waitcnt lgkmcnt(7)
	v_lshlrev_b32_e32 v16, 16, v16
	v_mul_f32_e32 v14, v14, v16
	v_cvt_pk_bf16_f32 v14, v14, s0
	ds_write_b16 v18, v14 offset:12288
	v_mul_f32_e32 v14, 0xbfb8aa3b, v15
	v_exp_f32_e32 v52, v14
	v_sub_f32_e32 v14, v20, v15
	v_add_f32_e32 v15, v42, v19
	v_mul_f32_e32 v16, 0x3fb8aa3b, v15
	v_exp_f32_e32 v16, v16
	s_waitcnt lgkmcnt(7)
	v_lshlrev_b32_e32 v17, 16, v17
	v_mul_f32_e32 v14, 0x3fb8aa3b, v14
	v_exp_f32_e32 v14, v14
	v_mul_f32_e32 v16, v16, v17
	v_cvt_pk_bf16_f32 v16, v16, s0
	ds_write_b16 v18, v16 offset:12688
	v_mul_f32_e32 v16, 0xbfb8aa3b, v15
	v_exp_f32_e32 v42, v16
	ds_read_u16 v16, v18 offset:37888
	ds_read_u16 v17, v18 offset:38288
	ds_read_u16 v53, v18 offset:38688
	ds_read_u16 v54, v18 offset:39088
	ds_read_u16 v55, v18 offset:39488
	ds_read_u16 v56, v18 offset:39888
	ds_read_u16 v57, v18 offset:40288
	ds_read_u16 v58, v18 offset:40688
	v_sub_f32_e32 v15, v20, v15
	s_waitcnt lgkmcnt(7)
	v_lshlrev_b32_e32 v16, 16, v16
	v_mul_f32_e32 v15, 0x3fb8aa3b, v15
	v_mul_f32_e32 v52, v52, v16
	v_exp_f32_e32 v15, v15
	v_cvt_pk_bf16_f32 v52, v52, s0
	v_add_f32_e32 v44, v44, v19
	ds_write_b16 v18, v52 offset:37888
	v_mul_f32_e32 v52, 0x3fb8aa3b, v44
	s_waitcnt lgkmcnt(7)
	v_lshlrev_b32_e32 v17, 16, v17
	v_exp_f32_e32 v52, v52
	v_mul_f32_e32 v42, v42, v17
	v_cvt_pk_bf16_f32 v42, v42, s0
	v_pk_mul_f32 v[14:15], v[14:15], v[16:17]
	v_add_f32_e32 v17, v45, v19
	ds_write_b16 v18, v42 offset:38288
	v_lshlrev_b32_e32 v16, 16, v21
	v_mul_f32_e32 v42, 0x3fb8aa3b, v17
	v_mul_f32_e32 v16, v52, v16
	v_exp_f32_e32 v42, v42
	v_cvt_pk_bf16_f32 v16, v16, s0
	ds_write_b16 v18, v16 offset:13088
	v_mul_f32_e32 v16, 0xbfb8aa3b, v44
	v_exp_f32_e32 v21, v16
	v_sub_f32_e32 v16, v20, v44
	v_lshlrev_b32_e32 v44, 16, v46
	v_mul_f32_e32 v42, v42, v44
	v_cvt_pk_bf16_f32 v42, v42, s0
	ds_write_b16 v18, v42 offset:13488
	v_mul_f32_e32 v42, 0xbfb8aa3b, v17
	v_exp_f32_e32 v42, v42
	s_waitcnt lgkmcnt(9)
	v_lshlrev_b32_e32 v44, 16, v53
	v_mul_f32_e32 v21, v21, v44
	v_sub_f32_e32 v17, v20, v17
	s_waitcnt lgkmcnt(8)
	v_lshlrev_b32_e32 v45, 16, v54
	v_cvt_pk_bf16_f32 v21, v21, s0
	v_mul_f32_e32 v16, 0x3fb8aa3b, v16
	v_mul_f32_e32 v17, 0x3fb8aa3b, v17
	ds_write_b16 v18, v21 offset:38688
	v_mul_f32_e32 v21, v42, v45
	v_add_f32_e32 v42, v83, v19
	v_exp_f32_e32 v16, v16
	v_exp_f32_e32 v17, v17
	v_mul_f32_e32 v46, 0x3fb8aa3b, v42
	v_exp_f32_e32 v46, v46
	v_cvt_pk_bf16_f32 v21, v21, s0
	ds_write_b16 v18, v21 offset:39088
	v_pk_mul_f32 v[16:17], v[16:17], v[44:45]
	v_lshlrev_b32_e32 v21, 16, v47
	v_add_f32_e32 v45, v85, v19
	v_mul_f32_e32 v21, v46, v21
	v_mul_f32_e32 v44, 0x3fb8aa3b, v45
	v_cvt_pk_bf16_f32 v21, v21, s0
	v_exp_f32_e32 v46, v44
	ds_write_b16 v18, v21 offset:13888
	v_mul_f32_e32 v21, 0xbfb8aa3b, v42
	v_sub_f32_e32 v42, v20, v42
	v_mul_f32_e32 v42, 0x3fb8aa3b, v42
	v_exp_f32_e32 v44, v42
	v_lshlrev_b32_e32 v42, 16, v48
	v_mul_f32_e32 v42, v46, v42
	v_exp_f32_e32 v21, v21
	v_cvt_pk_bf16_f32 v42, v42, s0
	ds_write_b16 v18, v42 offset:14288
	v_mul_f32_e32 v42, 0xbfb8aa3b, v45
	v_exp_f32_e32 v42, v42
	s_waitcnt lgkmcnt(11)
	v_lshlrev_b32_e32 v46, 16, v55
	v_mul_f32_e32 v21, v21, v46
	s_waitcnt lgkmcnt(10)
	v_lshlrev_b32_e32 v47, 16, v56
	v_cvt_pk_bf16_f32 v21, v21, s0
	ds_write_b16 v18, v21 offset:39488
	v_mul_f32_e32 v21, v42, v47
	v_add_f32_e32 v42, v86, v19
	v_mul_f32_e32 v48, 0x3fb8aa3b, v42
	v_exp_f32_e32 v48, v48
	v_cvt_pk_bf16_f32 v21, v21, s0
	ds_write_b16 v18, v21 offset:39888
	v_lshlrev_b32_e32 v21, 16, v50
	v_mul_f32_e32 v21, v48, v21
	v_sub_f32_e32 v45, v20, v45
	v_cvt_pk_bf16_f32 v21, v21, s0
	v_mul_f32_e32 v45, 0x3fb8aa3b, v45
	ds_write_b16 v18, v21 offset:14688
	v_mul_f32_e32 v21, 0xbfb8aa3b, v42
	v_add_f32_e32 v19, v49, v19
	v_exp_f32_e32 v45, v45
	v_exp_f32_e32 v48, v21
	v_sub_f32_e32 v21, v20, v42
	v_mul_f32_e32 v42, 0x3fb8aa3b, v19
	v_exp_f32_e32 v42, v42
	v_mul_f32_e32 v21, 0x3fb8aa3b, v21
	v_pk_mul_f32 v[44:45], v[44:45], v[46:47]
	v_exp_f32_e32 v46, v21
	v_lshlrev_b32_e32 v21, 16, v51
	v_mul_f32_e32 v21, v42, v21
	v_cvt_pk_bf16_f32 v21, v21, s0
	ds_write_b16 v18, v21 offset:15088
	v_mul_f32_e32 v21, 0xbfb8aa3b, v19
	v_exp_f32_e32 v42, v21
	v_sub_f32_e32 v19, v20, v19
	v_mul_f32_e32 v19, 0x3fb8aa3b, v19
	s_waitcnt lgkmcnt(13)
	v_lshlrev_b32_e32 v20, 16, v57
	v_exp_f32_e32 v47, v19
	v_mul_f32_e32 v19, v48, v20
	s_waitcnt lgkmcnt(12)
	v_lshlrev_b32_e32 v21, 16, v58
	v_cvt_pk_bf16_f32 v19, v19, s0
	ds_write_b16 v18, v19 offset:40288
	v_mul_f32_e32 v19, v42, v21
	v_cvt_pk_bf16_f32 v19, v19, s0
	ds_write_b16 v18, v19 offset:40688
	v_pk_mul_f32 v[18:19], v[46:47], v[20:21]
	v_cvt_pk_bf16_f32 v14, v14, v15
	v_cvt_pk_bf16_f32 v15, v16, v17
	v_cvt_pk_bf16_f32 v17, v18, v19
	v_mad_u32_u24 v18, v23, s66, 0
	v_lshlrev_b32_e32 v32, 1, v32
	v_add3_u32 v19, v18, v30, v31
	v_cvt_pk_bf16_f32 v16, v44, v45
	ds_write_b64 v19, v[14:15] offset:63488
	v_add_u32_e32 v14, v18, v32
	s_movk_i32 s24, 0xff74
	ds_write_b64 v14, v[16:17] offset:63488
	v_mad_i32_i24 v20, v23, s24, v18
	ds_read2st64_b32 v[14:15], v20 offset0:21 offset1:24
	ds_read2st64_b32 v[16:17], v20 offset0:27 offset1:30
	ds_read2st64_b32 v[18:19], v20 offset0:33 offset1:36
	ds_read2st64_b32 v[20:21], v20 offset0:39 offset1:42
	s_waitcnt lgkmcnt(3)
	v_add_f32_e32 v14, 0, v14
	v_add_f32_e32 v42, v14, v15
	s_waitcnt lgkmcnt(2)
	v_add_f32_e32 v42, v42, v16
	v_add_f32_e32 v42, v42, v17
	s_waitcnt lgkmcnt(1)
	v_add_f32_e32 v42, v42, v18
	v_add_f32_e32 v42, v42, v19
	s_waitcnt lgkmcnt(0)
	v_add_f32_e32 v42, v42, v20
	v_add_f32_e32 v44, v42, v21
	s_and_saveexec_b64 s[54:55], vcc
	s_cbranch_execz .LBB0_478
	v_mul_f32_e32 v42, 0x3fb8aa3b, v44
	v_exp_f32_e32 v42, v42
	global_store_dword v180, v42, s[52:53] offset:256 sc1
.LBB0_478:
	s_or_b64 exec, exec, s[54:55]
	v_cndmask_b32_e64 v14, 0, v14, s[8:9]
	v_add_f32_e32 v15, v15, v14
	v_cndmask_b32_e64 v14, v14, v15, s[10:11]
	v_add_f32_e32 v15, v16, v14
	v_cndmask_b32_e64 v14, v14, v15, s[12:13]
	v_add_f32_e32 v15, v17, v14
	v_cndmask_b32_e64 v14, v14, v15, s[14:15]
	v_add_f32_e32 v15, v18, v14
	v_cndmask_b32_e64 v14, v14, v15, s[16:17]
	v_add_f32_e32 v15, v19, v14
	v_cndmask_b32_e64 v14, v14, v15, s[18:19]
	v_add_f32_e32 v15, v20, v14
	v_cndmask_b32_e64 v14, v14, v15, s[20:21]
	v_add_f32_e32 v15, v21, v14
	v_or_b32_e32 v42, 64, v23
	v_cndmask_b32_e64 v19, v14, v15, s[22:23]
	v_lshlrev_b32_e32 v14, 1, v42
	v_add_f32_e32 v15, v37, v19
	v_add3_u32 v18, 0, v14, v40
	v_mul_f32_e32 v14, 0x3fb8aa3b, v15
	v_exp_f32_e32 v14, v14
	ds_read_u16 v16, v18 offset:12288
	ds_read_u16 v17, v18 offset:12688
	ds_read_u16 v20, v18 offset:13088
	ds_read_u16 v21, v18 offset:13488
	ds_read_u16 v37, v18 offset:13888
	ds_read_u16 v45, v18 offset:14288
	ds_read_u16 v46, v18 offset:14688
	ds_read_u16 v47, v18 offset:15088
	s_waitcnt lgkmcnt(7)
	v_lshlrev_b32_e32 v16, 16, v16
	v_add_f32_e32 v13, v13, v19
	v_mul_f32_e32 v14, v14, v16
	v_cvt_pk_bf16_f32 v14, v14, s0
	ds_write_b16 v18, v14 offset:12288
	v_mul_f32_e32 v14, 0xbfb8aa3b, v15
	v_exp_f32_e32 v48, v14
	v_sub_f32_e32 v14, v44, v15
	v_mul_f32_e32 v15, 0x3fb8aa3b, v13
	v_exp_f32_e32 v15, v15
	s_waitcnt lgkmcnt(7)
	v_lshlrev_b32_e32 v16, 16, v17
	v_mul_f32_e32 v14, 0x3fb8aa3b, v14
	v_exp_f32_e32 v14, v14
	v_mul_f32_e32 v15, v15, v16
	v_cvt_pk_bf16_f32 v15, v15, s0
	ds_write_b16 v18, v15 offset:12688
	v_mul_f32_e32 v15, 0xbfb8aa3b, v13
	v_sub_f32_e32 v13, v44, v13
	v_mul_f32_e32 v13, 0x3fb8aa3b, v13
	v_exp_f32_e32 v49, v15
	v_exp_f32_e32 v15, v13
	ds_read_u16 v13, v18 offset:37888
	ds_read_u16 v16, v18 offset:38288
	ds_read_u16 v50, v18 offset:38688
	ds_read_u16 v51, v18 offset:39088
	ds_read_u16 v52, v18 offset:39488
	ds_read_u16 v53, v18 offset:39888
	ds_read_u16 v54, v18 offset:40288
	ds_read_u16 v55, v18 offset:40688
	s_waitcnt lgkmcnt(6)
	v_lshlrev_b32_e32 v17, 16, v16
	v_lshlrev_b32_e32 v16, 16, v13
	v_mul_f32_e32 v13, v48, v16
	v_cvt_pk_bf16_f32 v13, v13, s0
	v_add_f32_e32 v35, v35, v19
	ds_write_b16 v18, v13 offset:37888
	v_mul_f32_e32 v13, v49, v17
	v_mul_f32_e32 v48, 0x3fb8aa3b, v35
	v_cvt_pk_bf16_f32 v13, v13, s0
	v_exp_f32_e32 v48, v48
	v_pk_mul_f32 v[14:15], v[14:15], v[16:17]
	v_add_f32_e32 v17, v36, v19
	ds_write_b16 v18, v13 offset:38288
	v_lshlrev_b32_e32 v13, 16, v20
	v_mul_f32_e32 v20, 0x3fb8aa3b, v17
	v_exp_f32_e32 v20, v20
	v_mul_f32_e32 v13, v48, v13
	v_cvt_pk_bf16_f32 v13, v13, s0
	v_lshlrev_b32_e32 v21, 16, v21
	ds_write_b16 v18, v13 offset:13088
	v_mul_f32_e32 v13, 0xbfb8aa3b, v35
	v_mul_f32_e32 v20, v20, v21
	v_exp_f32_e32 v13, v13
	v_cvt_pk_bf16_f32 v20, v20, s0
	ds_write_b16 v18, v20 offset:13488
	v_mul_f32_e32 v20, 0xbfb8aa3b, v17
	v_sub_f32_e32 v16, v44, v35
	v_exp_f32_e32 v35, v20
	s_waitcnt lgkmcnt(9)
	v_lshlrev_b32_e32 v20, 16, v50
	v_mul_f32_e32 v13, v13, v20
	s_waitcnt lgkmcnt(8)
	v_lshlrev_b32_e32 v21, 16, v51
	v_cvt_pk_bf16_f32 v13, v13, s0
	ds_write_b16 v18, v13 offset:38688
	v_mul_f32_e32 v13, v35, v21
	v_add_f32_e32 v35, v38, v19
	v_sub_f32_e32 v17, v44, v17
	v_mul_f32_e32 v36, 0x3fb8aa3b, v35
	v_mul_f32_e32 v16, 0x3fb8aa3b, v16
	v_mul_f32_e32 v17, 0x3fb8aa3b, v17
	v_exp_f32_e32 v36, v36
	v_exp_f32_e32 v16, v16
	v_exp_f32_e32 v17, v17
	v_cvt_pk_bf16_f32 v13, v13, s0
	ds_write_b16 v18, v13 offset:39088
	v_lshlrev_b32_e32 v13, 16, v37
	v_mul_f32_e32 v13, v36, v13
	v_pk_mul_f32 v[16:17], v[16:17], v[20:21]
	v_cvt_pk_bf16_f32 v13, v13, s0
	v_add_f32_e32 v21, v39, v19
	ds_write_b16 v18, v13 offset:13888
	v_mul_f32_e32 v13, 0xbfb8aa3b, v35
	v_sub_f32_e32 v20, v44, v35
	v_mul_f32_e32 v35, 0x3fb8aa3b, v21
	v_exp_f32_e32 v35, v35
	v_lshlrev_b32_e32 v36, 16, v45
	v_exp_f32_e32 v13, v13
	s_waitcnt lgkmcnt(9)
	v_lshlrev_b32_e32 v37, 16, v53
	v_mul_f32_e32 v35, v35, v36
	v_cvt_pk_bf16_f32 v35, v35, s0
	ds_write_b16 v18, v35 offset:14288
	v_mul_f32_e32 v35, 0xbfb8aa3b, v21
	v_exp_f32_e32 v35, v35
	v_lshlrev_b32_e32 v36, 16, v52
	v_mul_f32_e32 v13, v13, v36
	v_cvt_pk_bf16_f32 v13, v13, s0
	v_sub_f32_e32 v21, v44, v21
	ds_write_b16 v18, v13 offset:39488
	v_mul_f32_e32 v13, v35, v37
	v_add_f32_e32 v35, v41, v19
	v_mul_f32_e32 v20, 0x3fb8aa3b, v20
	v_mul_f32_e32 v21, 0x3fb8aa3b, v21
	v_mul_f32_e32 v38, 0x3fb8aa3b, v35
	v_exp_f32_e32 v20, v20
	v_exp_f32_e32 v21, v21
	v_exp_f32_e32 v38, v38
	v_cvt_pk_bf16_f32 v13, v13, s0
	ds_write_b16 v18, v13 offset:39888
	v_lshlrev_b32_e32 v13, 16, v46
	v_add_f32_e32 v19, v43, v19
	v_pk_mul_f32 v[20:21], v[20:21], v[36:37]
	v_mul_f32_e32 v13, v38, v13
	v_mul_f32_e32 v36, 0x3fb8aa3b, v19
	v_cvt_pk_bf16_f32 v13, v13, s0
	v_exp_f32_e32 v37, v36
	ds_write_b16 v18, v13 offset:14688
	v_mul_f32_e32 v13, 0xbfb8aa3b, v35
	v_sub_f32_e32 v35, v44, v35
	v_mul_f32_e32 v35, 0x3fb8aa3b, v35
	v_exp_f32_e32 v36, v35
	v_lshlrev_b32_e32 v35, 16, v47
	v_mul_f32_e32 v35, v37, v35
	v_exp_f32_e32 v13, v13
	v_cvt_pk_bf16_f32 v35, v35, s0
	ds_write_b16 v18, v35 offset:15088
	v_mul_f32_e32 v35, 0xbfb8aa3b, v19
	v_exp_f32_e32 v35, v35
	v_sub_f32_e32 v19, v44, v19
	v_mul_f32_e32 v19, 0x3fb8aa3b, v19
	s_waitcnt lgkmcnt(13)
	v_lshlrev_b32_e32 v38, 16, v54
	v_exp_f32_e32 v37, v19
	v_mul_f32_e32 v13, v13, v38
	s_waitcnt lgkmcnt(12)
	v_lshlrev_b32_e32 v39, 16, v55
	v_cvt_pk_bf16_f32 v13, v13, s0
	ds_write_b16 v18, v13 offset:40288
	v_mul_f32_e32 v13, v35, v39
	v_cvt_pk_bf16_f32 v13, v13, s0
	ds_write_b16 v18, v13 offset:40688
	v_pk_mul_f32 v[18:19], v[36:37], v[38:39]
	v_mad_u32_u24 v13, v42, s66, 0
	v_cvt_pk_bf16_f32 v14, v14, v15
	v_cvt_pk_bf16_f32 v15, v16, v17
	v_cvt_pk_bf16_f32 v16, v20, v21
	v_cvt_pk_bf16_f32 v17, v18, v19
	v_add3_u32 v18, v13, v30, v31
	v_add_u32_e32 v13, v13, v32
	ds_write_b64 v18, v[14:15] offset:63488
	ds_write_b64 v13, v[16:17] offset:63488
	ds_read2st64_b32 v[14:15], v12 offset0:22 offset1:25
	ds_read2st64_b32 v[16:17], v12 offset0:28 offset1:31
	ds_read2st64_b32 v[18:19], v12 offset0:34 offset1:37
	ds_read2st64_b32 v[12:13], v12 offset0:40 offset1:43
	s_waitcnt lgkmcnt(3)
	v_add_f32_e32 v14, 0, v14
	v_add_f32_e32 v20, v14, v15
	s_waitcnt lgkmcnt(2)
	v_add_f32_e32 v20, v20, v16
	v_add_f32_e32 v20, v20, v17
	s_waitcnt lgkmcnt(1)
	v_add_f32_e32 v20, v20, v18
	v_add_f32_e32 v20, v20, v19
	s_waitcnt lgkmcnt(0)
	v_add_f32_e32 v20, v20, v12
	v_add_f32_e32 v21, v20, v13
	s_and_saveexec_b64 s[54:55], vcc
	s_cbranch_execz .LBB0_473
	v_mul_f32_e32 v20, 0x3fb8aa3b, v21
	v_exp_f32_e32 v20, v20
	global_store_dword v180, v20, s[52:53] offset:512 sc1
	s_branch .LBB0_473

.LBB0_756:
	v_ashrrev_i32_e32 v73, 31, v72
	v_lshlrev_b64 v[86:87], 12, v[72:73]
	v_lshl_add_u64 v[32:33], v[74:75], 0, v[86:87]
	global_load_dwordx2 v[56:57], v[32:33], off nt
	global_load_dwordx2 v[58:59], v[32:33], off offset:512 nt
	global_load_dwordx2 v[60:61], v[32:33], off offset:1024 nt
	global_load_dwordx2 v[62:63], v[32:33], off offset:1536 nt
	global_load_dwordx2 v[64:65], v[32:33], off offset:2560 nt
	global_load_dwordx2 v[66:67], v[32:33], off offset:2048 nt
	global_load_dwordx2 v[68:69], v[32:33], off offset:3584 nt
	global_load_dwordx2 v[84:85], v[32:33], off offset:3072 nt
	v_lshlrev_b64 v[88:89], 13, v[72:73]
	v_lshl_add_u64 v[32:33], v[80:81], 0, v[88:89]
	v_add_co_u32_e32 v94, vcc, s3, v32
	global_load_dwordx4 v[52:55], v[32:33], off nt
	global_load_dwordx4 v[48:51], v[32:33], off offset:1024 nt
	global_load_dwordx4 v[44:47], v[32:33], off offset:2048 nt
	global_load_dwordx4 v[40:43], v[32:33], off offset:3072 nt
	v_addc_co_u32_e32 v95, vcc, 0, v33, vcc
	global_load_dwordx4 v[36:39], v[94:95], off nt
	global_load_dwordx4 v[32:35], v[94:95], off offset:1024 nt
	global_load_dwordx4 v[90:93], v[94:95], off offset:2048 nt
	v_lshl_add_u64 v[88:89], v[76:77], 0, v[88:89]
	global_load_dwordx4 v[94:97], v[94:95], off offset:3072 nt
	v_lshl_add_u64 v[86:87], v[78:79], 0, v[86:87]
	s_waitcnt vmcnt(0)
	v_and_b32_e32 v99, 0xffff0000, v56
	v_and_b32_e32 v101, 0xffff0000, v58
	v_lshlrev_b32_e32 v98, 16, v56
	v_lshlrev_b32_e32 v100, 16, v58
	v_and_b32_e32 v103, 0xffff0000, v60
	v_lshlrev_b32_e32 v56, 16, v57
	v_lshlrev_b32_e32 v71, 16, v68
	v_and_b32_e32 v115, 0xffff0000, v68
	v_lshlrev_b32_e32 v117, 16, v69
	v_and_b32_e32 v119, 0xffff0000, v69
	v_mul_f32_e32 v68, v99, v99
	v_mul_f32_e32 v69, v101, v101
	v_lshlrev_b32_e32 v58, 16, v59
	v_lshlrev_b32_e32 v102, 16, v60
	v_and_b32_e32 v105, 0xffff0000, v62
	v_mul_f32_e32 v73, v103, v103
	v_fmac_f32_e32 v68, v98, v98
	v_fmac_f32_e32 v69, v100, v100
	v_and_b32_e32 v57, 0xffff0000, v57
	v_and_b32_e32 v59, 0xffff0000, v59
	v_lshlrev_b32_e32 v60, 16, v61
	v_lshlrev_b32_e32 v104, 16, v62
	v_and_b32_e32 v109, 0xffff0000, v64
	v_and_b32_e32 v108, 0xffff0000, v66
	v_lshlrev_b32_e32 v70, 16, v84
	v_and_b32_e32 v114, 0xffff0000, v84
	v_mul_f32_e32 v84, v105, v105
	v_fmac_f32_e32 v73, v102, v102
	v_fmac_f32_e32 v68, v56, v56
	v_fmac_f32_e32 v69, v58, v58
	v_and_b32_e32 v61, 0xffff0000, v61
	v_lshlrev_b32_e32 v62, 16, v63
	v_lshlrev_b32_e32 v107, 16, v64
	v_lshlrev_b32_e32 v106, 16, v66
	v_lshlrev_b32_e32 v111, 16, v65
	v_and_b32_e32 v113, 0xffff0000, v65
	v_pk_mul_f32 v[64:65], v[108:109], v[108:109]
	v_fmac_f32_e32 v84, v104, v104
	v_fmac_f32_e32 v73, v60, v60
	v_fmac_f32_e32 v68, v57, v57
	v_fmac_f32_e32 v69, v59, v59
	v_and_b32_e32 v63, 0xffff0000, v63
	v_lshlrev_b32_e32 v110, 16, v67
	v_pk_fma_f32 v[64:65], v[106:107], v[106:107], v[64:65]
	v_fmac_f32_e32 v84, v62, v62
	v_fmac_f32_e32 v73, v61, v61
	v_add_f32_e32 v68, v68, v69
	v_and_b32_e32 v112, 0xffff0000, v67
	v_pk_mul_f32 v[66:67], v[114:115], v[114:115]
	v_pk_fma_f32 v[64:65], v[110:111], v[110:111], v[64:65]
	v_fmac_f32_e32 v84, v63, v63
	v_add_f32_e32 v68, v68, v73
	v_lshlrev_b32_e32 v116, 16, v85
	v_pk_fma_f32 v[66:67], v[70:71], v[70:71], v[66:67]
	v_pk_fma_f32 v[64:65], v[112:113], v[112:113], v[64:65]
	v_add_f32_e32 v68, v68, v84
	v_and_b32_e32 v118, 0xffff0000, v85
	v_pk_fma_f32 v[66:67], v[116:117], v[116:117], v[66:67]
	v_add_f32_e32 v64, v68, v64
	v_pk_fma_f32 v[66:67], v[118:119], v[118:119], v[66:67]
	v_add_f32_e32 v64, v64, v65
	v_add_f32_e32 v64, v64, v66
	v_add_f32_e32 v64, v64, v67
	ds_bpermute_b32 v65, v83, v64
	v_mov_b32_e32 v124, v106
	v_mov_b32_e32 v126, v110
	v_mov_b32_e32 v127, v112
	v_mov_b32_e32 v112, v111
	s_waitcnt lgkmcnt(0)
	v_add_f32_e32 v64, v64, v65
	ds_bpermute_b32 v65, v132, v64
	s_waitcnt lgkmcnt(0)
	v_add_f32_e32 v64, v64, v65
	ds_bpermute_b32 v65, v133, v64
	s_waitcnt lgkmcnt(0)
	v_add_f32_e32 v66, v64, v65
	v_add_u32_e32 v64, 1, v72
	ds_bpermute_b32 v67, v134, v66
	v_ashrrev_i32_e32 v65, 31, v64
	v_lshlrev_b64 v[84:85], 12, v[64:65]
	v_lshl_add_u64 v[68:69], v[74:75], 0, v[84:85]
	global_load_dwordx2 v[120:121], v[68:69], off nt
	global_load_dwordx2 v[122:123], v[68:69], off offset:512 nt
	global_load_dwordx2 v[138:139], v[68:69], off offset:1024 nt
	global_load_dwordx2 v[140:141], v[68:69], off offset:1536 nt
	s_waitcnt lgkmcnt(0)
	v_add_f32_e32 v66, v66, v67
	ds_bpermute_b32 v67, v135, v66
	v_add_u32_e32 v72, s13, v72
	s_waitcnt lgkmcnt(0)
	v_add_f32_e32 v73, v66, v67
	global_load_dwordx2 v[142:143], v[68:69], off offset:2048 nt
	global_load_dwordx2 v[144:145], v[68:69], off offset:2560 nt
	global_load_dwordx2 v[66:67], v[68:69], off offset:3072 nt
	s_nop 0
	global_load_dwordx2 v[68:69], v[68:69], off offset:3584 nt
	ds_bpermute_b32 v125, v136, v73
	s_waitcnt lgkmcnt(0)
	v_add_f32_e32 v73, v73, v125
	v_fmamk_f32 v73, v73, 0x3a000000, v82
	v_mul_f32_e32 v106, 0x4b800000, v73
	v_cmp_gt_f32_e32 vcc, s14, v73
	v_mov_b32_e32 v125, v108
	v_mov_b32_e32 v108, v107
	v_cndmask_b32_e32 v73, v73, v106, vcc
	v_rsq_f32_e32 v73, v73
	s_waitcnt vmcnt(7)
	v_and_b32_e32 v164, 0xffff0000, v120
	v_mul_f32_e32 v106, 0x45800000, v73
	v_cndmask_b32_e32 v106, v73, v106, vcc
	v_pk_mul_f32 v[98:99], v[98:99], v[106:107] op_sel_hi:[1,0]
	v_pk_mul_f32 v[102:103], v[102:103], v[106:107] op_sel_hi:[1,0]
	v_pk_mul_f32 v[124:125], v[124:125], v[106:107] op_sel_hi:[1,0]
	v_pk_mul_f32 v[56:57], v[56:57], v[106:107] op_sel_hi:[1,0]
	v_pk_mul_f32 v[128:129], v[60:61], v[106:107] op_sel_hi:[1,0]
	v_pk_mul_f32 v[126:127], v[126:127], v[106:107] op_sel_hi:[1,0]
	v_pk_fma_f32 v[60:61], v[0:1], v[98:99], v[52:53]
	v_pk_fma_f32 v[52:53], v[8:9], v[102:103], v[44:45]
	v_pk_fma_f32 v[44:45], v[16:17], v[124:125], v[36:37]
	v_pk_mul_f32 v[36:37], v[108:109], v[106:107] op_sel_hi:[1,0]
	v_pk_mul_f32 v[130:131], v[62:63], v[106:107] op_sel_hi:[1,0]
	v_pk_fma_f32 v[62:63], v[2:3], v[56:57], v[54:55]
	v_pk_fma_f32 v[54:55], v[10:11], v[128:129], v[46:47]
	v_pk_fma_f32 v[46:47], v[18:19], v[126:127], v[38:39]
	v_pk_mul_f32 v[38:39], v[112:113], v[106:107] op_sel_hi:[1,0]
	v_pk_fma_f32 v[32:33], v[20:21], v[36:37], v[32:33]
	v_pk_mul_f32 v[100:101], v[100:101], v[106:107] op_sel_hi:[1,0]
	v_pk_fma_f32 v[34:35], v[22:23], v[38:39], v[34:35]
	v_mov_b32_e32 v38, v33
	v_mov_b32_e32 v39, v45
	v_pk_mul_f32 v[58:59], v[58:59], v[106:107] op_sel_hi:[1,0]
	v_pk_fma_f32 v[56:57], v[4:5], v[100:101], v[48:49]
	v_mov_b32_e32 v36, v32
	v_mov_b32_e32 v37, v44
	v_pk_mul_f32 v[38:39], v[38:39], v[38:39]
	v_pk_fma_f32 v[58:59], v[6:7], v[58:59], v[50:51]
	v_pk_fma_f32 v[50:51], v[14:15], v[130:131], v[42:43]
	v_pk_fma_f32 v[36:37], v[36:37], v[36:37], v[38:39]
	v_mov_b32_e32 v38, v34
	v_mov_b32_e32 v39, v46
	s_waitcnt vmcnt(6)
	v_and_b32_e32 v130, 0xffff0000, v122
	v_mov_b32_e32 v165, v61
	v_mov_b32_e32 v131, v57
	v_pk_fma_f32 v[36:37], v[38:39], v[38:39], v[36:37]
	v_mov_b32_e32 v38, v35
	v_mov_b32_e32 v39, v47
	v_lshlrev_b32_e32 v162, 16, v120
	v_lshlrev_b32_e32 v126, 16, v122
	v_mov_b32_e32 v163, v60
	v_pk_mul_f32 v[100:101], v[164:165], v[164:165]
	v_mov_b32_e32 v127, v56
	v_pk_mul_f32 v[102:103], v[130:131], v[130:131]
	v_pk_mul_f32 v[104:105], v[104:105], v[106:107] op_sel_hi:[1,0]
	v_pk_fma_f32 v[146:147], v[38:39], v[38:39], v[36:37]
	v_mov_b32_e32 v36, v70
	v_mov_b32_e32 v37, v114
	v_mov_b32_e32 v114, v71
	v_lshlrev_b32_e32 v166, 16, v121
	v_lshlrev_b32_e32 v124, 16, v123
	v_pk_fma_f32 v[100:101], v[162:163], v[162:163], v[100:101]
	v_mov_b32_e32 v167, v62
	v_pk_fma_f32 v[102:103], v[126:127], v[126:127], v[102:103]
	v_mov_b32_e32 v125, v58
	v_pk_fma_f32 v[48:49], v[12:13], v[104:105], v[40:41]
	v_pk_mul_f32 v[36:37], v[36:37], v[106:107] op_sel_hi:[1,0]
	v_pk_mul_f32 v[40:41], v[114:115], v[106:107] op_sel_hi:[1,0]
	v_and_b32_e32 v168, 0xffff0000, v121
	v_and_b32_e32 v128, 0xffff0000, v123
	v_pk_fma_f32 v[100:101], v[166:167], v[166:167], v[100:101]
	v_mov_b32_e32 v169, v63
	v_pk_fma_f32 v[102:103], v[124:125], v[124:125], v[102:103]
	v_mov_b32_e32 v129, v59
	v_mov_b32_e32 v38, v116
	v_mov_b32_e32 v39, v118
	v_pk_fma_f32 v[36:37], v[24:25], v[36:37], v[90:91]
	v_mov_b32_e32 v118, v117
	v_pk_fma_f32 v[40:41], v[28:29], v[40:41], v[94:95]
	s_waitcnt vmcnt(5)
	v_and_b32_e32 v122, 0xffff0000, v138
	v_pk_fma_f32 v[100:101], v[168:169], v[168:169], v[100:101]
	v_pk_fma_f32 v[102:103], v[128:129], v[128:129], v[102:103]
	v_mov_b32_e32 v123, v53
	v_pk_mul_f32 v[38:39], v[38:39], v[106:107] op_sel_hi:[1,0]
	v_pk_mul_f32 v[42:43], v[118:119], v[106:107] op_sel_hi:[1,0]
	v_mov_b32_e32 v90, v41
	v_mov_b32_e32 v91, v37
	v_lshlrev_b32_e32 v118, 16, v138
	v_pk_add_f32 v[100:101], v[100:101], v[102:103]
	v_mov_b32_e32 v119, v52
	v_pk_mul_f32 v[102:103], v[122:123], v[122:123]
	v_pk_fma_f32 v[38:39], v[26:27], v[38:39], v[92:93]
	v_pk_fma_f32 v[42:43], v[30:31], v[42:43], v[96:97]
	v_mov_b32_e32 v70, v40
	v_mov_b32_e32 v71, v36
	v_pk_mul_f32 v[90:91], v[90:91], v[90:91]
	v_lshlrev_b32_e32 v116, 16, v139
	v_pk_fma_f32 v[102:103], v[118:119], v[118:119], v[102:103]
	v_mov_b32_e32 v117, v54
	v_pk_fma_f32 v[70:71], v[70:71], v[70:71], v[90:91]
	v_mov_b32_e32 v90, v42
	v_mov_b32_e32 v91, v38
	v_and_b32_e32 v120, 0xffff0000, v139
	v_pk_fma_f32 v[102:103], v[116:117], v[116:117], v[102:103]
	v_mov_b32_e32 v121, v55
	v_pk_fma_f32 v[70:71], v[90:91], v[90:91], v[70:71]
	v_mov_b32_e32 v90, v43
	v_mov_b32_e32 v91, v39
	s_waitcnt vmcnt(4)
	v_and_b32_e32 v114, 0xffff0000, v140
	s_waitcnt vmcnt(2)
	v_and_b32_e32 v95, 0xffff0000, v144
	v_and_b32_e32 v94, 0xffff0000, v142
	v_pk_fma_f32 v[102:103], v[120:121], v[120:121], v[102:103]
	v_mov_b32_e32 v115, v49
	v_pk_fma_f32 v[70:71], v[90:91], v[90:91], v[70:71]
	v_lshlrev_b32_e32 v110, 16, v140
	v_lshlrev_b32_e32 v91, 16, v144
	v_lshlrev_b32_e32 v90, 16, v142
	v_pk_mul_f32 v[92:93], v[94:95], v[94:95]
	v_pk_add_f32 v[100:101], v[102:103], v[100:101]
	v_mov_b32_e32 v111, v48
	v_pk_mul_f32 v[102:103], v[114:115], v[114:115]
	v_lshlrev_b32_e32 v108, 16, v141
	v_lshlrev_b32_e32 v97, 16, v145
	v_lshlrev_b32_e32 v96, 16, v143
	v_pk_fma_f32 v[92:93], v[90:91], v[90:91], v[92:93]
	v_pk_fma_f32 v[102:103], v[110:111], v[110:111], v[102:103]
	v_mov_b32_e32 v109, v50
	v_and_b32_e32 v112, 0xffff0000, v141
	v_and_b32_e32 v99, 0xffff0000, v145
	v_and_b32_e32 v98, 0xffff0000, v143
	v_pk_fma_f32 v[92:93], v[96:97], v[96:97], v[92:93]
	v_pk_fma_f32 v[102:103], v[108:109], v[108:109], v[102:103]
	v_mov_b32_e32 v113, v51
	v_pk_fma_f32 v[92:93], v[98:99], v[98:99], v[92:93]
	v_pk_fma_f32 v[102:103], v[112:113], v[112:113], v[102:103]
	s_waitcnt vmcnt(1)
	v_lshlrev_b32_e32 v104, 16, v67
	v_pk_add_f32 v[100:101], v[102:103], v[100:101]
	v_mov_b32_e32 v102, v92
	v_mov_b32_e32 v103, v147
	v_pk_add_f32 v[138:139], v[100:101], v[102:103]
	s_waitcnt vmcnt(0)
	v_and_b32_e32 v103, 0xffff0000, v68
	v_and_b32_e32 v102, 0xffff0000, v66
	v_lshlrev_b32_e32 v101, 16, v68
	v_lshlrev_b32_e32 v100, 16, v66
	v_and_b32_e32 v106, 0xffff0000, v67
	v_pk_mul_f32 v[66:67], v[102:103], v[102:103]
	v_lshlrev_b32_e32 v105, 16, v69
	v_pk_fma_f32 v[66:67], v[100:101], v[100:101], v[66:67]
	v_and_b32_e32 v107, 0xffff0000, v69
	v_pk_fma_f32 v[66:67], v[104:105], v[104:105], v[66:67]
	v_pk_mov_b32 v[68:69], v[92:93], v[146:147] op_sel:[1,0]
	v_pk_fma_f32 v[66:67], v[106:107], v[106:107], v[66:67]
	v_pk_add_f32 v[68:69], v[138:139], v[68:69]
	v_mov_b32_e32 v92, v66
	v_mov_b32_e32 v93, v71
	v_pk_add_f32 v[68:69], v[68:69], v[92:93]
	v_lshlrev_b64 v[92:93], 13, v[64:65]
	v_lshl_add_u64 v[64:65], v[80:81], 0, v[92:93]
	v_pk_mov_b32 v[66:67], v[66:67], v[70:71] op_sel:[1,0]
	global_load_dwordx4 v[138:141], v[64:65], off nt
	global_load_dwordx4 v[142:145], v[64:65], off offset:1024 nt
	global_load_dwordx4 v[146:149], v[64:65], off offset:2048 nt
	global_load_dwordx4 v[150:153], v[64:65], off offset:3072 nt
	v_pk_add_f32 v[66:67], v[68:69], v[66:67]
	ds_bpermute_b32 v69, v83, v67
	ds_bpermute_b32 v68, v83, v66
	v_add_co_u32_e32 v64, vcc, s3, v64
	v_mov_b32_e32 v163, v164
	s_nop 0
	v_addc_co_u32_e32 v65, vcc, 0, v65, vcc
	s_waitcnt lgkmcnt(0)
	v_pk_add_f32 v[66:67], v[66:67], v[68:69]
	ds_bpermute_b32 v69, v132, v67
	ds_bpermute_b32 v68, v132, v66
	v_mov_b32_e32 v127, v130
	v_mov_b32_e32 v167, v168
	v_mov_b32_e32 v125, v128
	v_mov_b32_e32 v119, v122
	s_waitcnt lgkmcnt(0)
	v_pk_add_f32 v[66:67], v[66:67], v[68:69]
	ds_bpermute_b32 v69, v133, v67
	ds_bpermute_b32 v68, v133, v66
	v_mov_b32_e32 v117, v120
	v_mov_b32_e32 v111, v114
	v_mov_b32_e32 v109, v112
	s_waitcnt lgkmcnt(0)
	v_pk_add_f32 v[170:171], v[66:67], v[68:69]
	global_load_dwordx4 v[154:157], v[64:65], off nt
	global_load_dwordx4 v[158:161], v[64:65], off offset:1024 nt
	global_load_dwordx4 v[68:71], v[64:65], off offset:2048 nt
	s_nop 0
	global_load_dwordx4 v[64:67], v[64:65], off offset:3072 nt
	ds_bpermute_b32 v173, v134, v171
	ds_bpermute_b32 v172, v134, v170
	global_store_dwordx4 v[88:89], v[60:63], off nt sc1
	global_store_dwordx4 v[88:89], v[56:59], off offset:1024 nt sc1
	global_store_dwordx4 v[88:89], v[52:55], off offset:2048 nt sc1
	global_store_dwordx4 v[88:89], v[48:51], off offset:3072 nt sc1
	v_add_co_u32_e32 v88, vcc, s3, v88
	s_waitcnt lgkmcnt(0)
	v_pk_add_f32 v[170:171], v[170:171], v[172:173]
	ds_bpermute_b32 v173, v135, v171
	ds_bpermute_b32 v172, v135, v170
	v_addc_co_u32_e32 v89, vcc, 0, v89, vcc
	global_store_dwordx4 v[88:89], v[44:47], off nt sc1
	global_store_dwordx4 v[88:89], v[32:35], off offset:1024 nt sc1
	global_store_dwordx4 v[88:89], v[36:39], off offset:2048 nt sc1
	global_store_dwordx4 v[88:89], v[40:43], off offset:3072 nt sc1
	s_waitcnt lgkmcnt(0)
	v_pk_add_f32 v[170:171], v[170:171], v[172:173]
	ds_bpermute_b32 v173, v136, v171
	ds_bpermute_b32 v172, v136, v170
	s_waitcnt lgkmcnt(0)
	v_pk_add_f32 v[170:171], v[170:171], v[172:173]
	s_nop 0
	v_pk_fma_f32 v[170:171], v[170:171], s[12:13], v[82:83] op_sel_hi:[1,0,0]
	s_nop 0
	v_mul_f32_e32 v73, 0x4b800000, v171
	v_cmp_gt_f32_e32 vcc, s14, v171
	s_nop 1
	v_cndmask_b32_e32 v73, v171, v73, vcc
	v_rsq_f32_e32 v73, v73
	s_nop 0
	v_mul_f32_e32 v88, 0x45800000, v73
	v_cndmask_b32_e32 v88, v73, v88, vcc
	v_pk_mul_f32 v[44:45], v[44:45], v[88:89] op_sel_hi:[1,0]
	v_pk_mul_f32 v[48:49], v[48:49], v[88:89] op_sel_hi:[1,0]
	v_pk_mul_f32 v[50:51], v[50:51], v[88:89] op_sel_hi:[1,0]
	v_cvt_pk_bf16_f32 v44, v44, v45
	v_mul_f32_e32 v45, 0x4b800000, v170
	v_cmp_gt_f32_e32 vcc, s14, v170
	v_cvt_pk_bf16_f32 v48, v48, v49
	v_cvt_pk_bf16_f32 v49, v50, v51
	v_cndmask_b32_e32 v45, v170, v45, vcc
	global_store_dwordx2 v[86:87], v[48:49], off offset:1536 sc1
	v_rsq_f32_e32 v48, v45
	v_pk_mul_f32 v[46:47], v[46:47], v[88:89] op_sel_hi:[1,0]
	v_pk_mul_f32 v[52:53], v[52:53], v[88:89] op_sel_hi:[1,0]
	v_cvt_pk_bf16_f32 v45, v46, v47
	global_store_dwordx2 v[86:87], v[44:45], off offset:2048 sc1
	v_mul_f32_e32 v44, 0x45800000, v48
	v_cndmask_b32_e32 v170, v48, v44, vcc
	v_pk_mul_f32 v[54:55], v[54:55], v[88:89] op_sel_hi:[1,0]
	v_pk_mul_f32 v[44:45], v[162:163], v[170:171] op_sel_hi:[1,0]
	v_pk_mul_f32 v[48:49], v[126:127], v[170:171] op_sel_hi:[1,0]
	v_cvt_pk_bf16_f32 v52, v52, v53
	v_cvt_pk_bf16_f32 v53, v54, v55
	s_waitcnt vmcnt(17)
	v_pk_fma_f32 v[44:45], v[0:1], v[44:45], v[138:139]
	s_waitcnt vmcnt(16)
	v_pk_fma_f32 v[48:49], v[4:5], v[48:49], v[142:143]
	global_store_dwordx2 v[86:87], v[52:53], off offset:1024 sc1
	v_pk_mul_f32 v[46:47], v[166:167], v[170:171] op_sel_hi:[1,0]
	v_mul_f32_e32 v52, v45, v45
	v_pk_mul_f32 v[50:51], v[124:125], v[170:171] op_sel_hi:[1,0]
	v_mul_f32_e32 v53, v49, v49
	v_pk_fma_f32 v[46:47], v[2:3], v[46:47], v[140:141]
	v_fmac_f32_e32 v52, v44, v44
	v_pk_fma_f32 v[50:51], v[6:7], v[50:51], v[144:145]
	v_fmac_f32_e32 v53, v48, v48
	v_pk_mul_f32 v[56:57], v[56:57], v[88:89] op_sel_hi:[1,0]
	v_pk_mul_f32 v[58:59], v[58:59], v[88:89] op_sel_hi:[1,0]
	v_fmac_f32_e32 v52, v46, v46
	v_fmac_f32_e32 v53, v50, v50
	v_cvt_pk_bf16_f32 v56, v56, v57
	v_cvt_pk_bf16_f32 v57, v58, v59
	v_fmac_f32_e32 v52, v47, v47
	v_fmac_f32_e32 v53, v51, v51
	global_store_dwordx2 v[86:87], v[56:57], off offset:512 sc1
	v_add_f32_e32 v56, v52, v53
	v_pk_mul_f32 v[52:53], v[118:119], v[170:171] op_sel_hi:[1,0]
	v_pk_mul_f32 v[54:55], v[116:117], v[170:171] op_sel_hi:[1,0]
	s_waitcnt vmcnt(17)
	v_pk_fma_f32 v[52:53], v[8:9], v[52:53], v[146:147]
	v_pk_fma_f32 v[54:55], v[10:11], v[54:55], v[148:149]
	v_mul_f32_e32 v57, v53, v53
	v_fmac_f32_e32 v57, v52, v52
	v_pk_mul_f32 v[60:61], v[60:61], v[88:89] op_sel_hi:[1,0]
	v_pk_mul_f32 v[62:63], v[62:63], v[88:89] op_sel_hi:[1,0]
	v_fmac_f32_e32 v57, v54, v54
	v_cvt_pk_bf16_f32 v60, v60, v61
	v_cvt_pk_bf16_f32 v61, v62, v63
	v_fmac_f32_e32 v57, v55, v55
	global_store_dwordx2 v[86:87], v[60:61], off sc1
	v_add_f32_e32 v60, v57, v56
	v_pk_mul_f32 v[56:57], v[110:111], v[170:171] op_sel_hi:[1,0]
	v_pk_mul_f32 v[58:59], v[108:109], v[170:171] op_sel_hi:[1,0]
	s_waitcnt vmcnt(17)
	v_pk_fma_f32 v[56:57], v[12:13], v[56:57], v[150:151]
	v_pk_fma_f32 v[58:59], v[14:15], v[58:59], v[152:153]
	v_mul_f32_e32 v61, v57, v57
	v_fmac_f32_e32 v61, v56, v56
	v_fmac_f32_e32 v61, v58, v58
	v_fmac_f32_e32 v61, v59, v59
	v_add_f32_e32 v73, v61, v60
	v_mov_b32_e32 v60, v90
	v_mov_b32_e32 v61, v94
	v_mov_b32_e32 v63, v98
	v_mov_b32_e32 v94, v91
	v_mov_b32_e32 v98, v97
	v_pk_mul_f32 v[60:61], v[60:61], v[170:171] op_sel_hi:[1,0]
	v_pk_mul_f32 v[90:91], v[94:95], v[170:171] op_sel_hi:[1,0]
	v_pk_mul_f32 v[94:95], v[98:99], v[170:171] op_sel_hi:[1,0]
	v_mov_b32_e32 v62, v96
	s_waitcnt vmcnt(16)
	v_pk_fma_f32 v[60:61], v[16:17], v[60:61], v[154:155]
	s_waitcnt vmcnt(15)
	v_pk_fma_f32 v[96:97], v[22:23], v[94:95], v[160:161]
	v_pk_fma_f32 v[94:95], v[20:21], v[90:91], v[158:159]
	v_pk_mul_f32 v[62:63], v[62:63], v[170:171] op_sel_hi:[1,0]
	v_mov_b32_e32 v98, v95
	v_mov_b32_e32 v99, v61
	v_pk_fma_f32 v[62:63], v[18:19], v[62:63], v[156:157]
	v_mov_b32_e32 v90, v94
	v_mov_b32_e32 v91, v60
	v_pk_mul_f32 v[98:99], v[98:99], v[98:99]
	s_nop 0
	v_pk_fma_f32 v[90:91], v[90:91], v[90:91], v[98:99]
	v_mov_b32_e32 v98, v96
	v_mov_b32_e32 v99, v62
	v_pk_fma_f32 v[90:91], v[98:99], v[98:99], v[90:91]
	v_mov_b32_e32 v98, v97
	v_mov_b32_e32 v99, v63
	v_pk_fma_f32 v[90:91], v[98:99], v[98:99], v[90:91]
	v_mov_b32_e32 v98, v104
	v_add_f32_e32 v73, v91, v73
	v_add_f32_e32 v73, v90, v73
	v_mov_b32_e32 v90, v100
	v_mov_b32_e32 v91, v102
	v_pk_mul_f32 v[90:91], v[90:91], v[170:171] op_sel_hi:[1,0]
	v_mov_b32_e32 v99, v106
	v_mov_b32_e32 v102, v101
	v_pk_mul_f32 v[98:99], v[98:99], v[170:171] op_sel_hi:[1,0]
	s_waitcnt vmcnt(14)
	v_pk_fma_f32 v[68:69], v[24:25], v[90:91], v[68:69]
	v_pk_mul_f32 v[90:91], v[102:103], v[170:171] op_sel_hi:[1,0]
	v_mov_b32_e32 v106, v105
	v_pk_fma_f32 v[70:71], v[26:27], v[98:99], v[70:71]
	v_pk_mul_f32 v[98:99], v[106:107], v[170:171] op_sel_hi:[1,0]
	s_waitcnt vmcnt(13)
	v_pk_fma_f32 v[64:65], v[28:29], v[90:91], v[64:65]
	v_pk_fma_f32 v[66:67], v[30:31], v[98:99], v[66:67]
	v_mov_b32_e32 v98, v65
	v_mov_b32_e32 v99, v69
	v_mov_b32_e32 v90, v64
	v_mov_b32_e32 v91, v68
	v_pk_mul_f32 v[98:99], v[98:99], v[98:99]
	s_nop 0
	v_pk_fma_f32 v[90:91], v[90:91], v[90:91], v[98:99]
	v_mov_b32_e32 v98, v66
	v_mov_b32_e32 v99, v70
	v_pk_fma_f32 v[90:91], v[98:99], v[98:99], v[90:91]
	v_mov_b32_e32 v98, v67
	v_mov_b32_e32 v99, v71
	v_pk_fma_f32 v[90:91], v[98:99], v[98:99], v[90:91]
	s_nop 0
	v_add_f32_e32 v73, v91, v73
	v_add_f32_e32 v73, v90, v73
	ds_bpermute_b32 v89, v83, v73
	s_waitcnt lgkmcnt(0)
	v_add_f32_e32 v73, v73, v89
	v_pk_mul_f32 v[32:33], v[32:33], v[88:89] op_sel_hi:[1,0]
	v_pk_mul_f32 v[34:35], v[34:35], v[88:89] op_sel_hi:[1,0]
	ds_bpermute_b32 v89, v132, v73
	v_cvt_pk_bf16_f32 v32, v32, v33
	v_cvt_pk_bf16_f32 v33, v34, v35
	global_store_dwordx2 v[86:87], v[32:33], off offset:2560 sc1
	s_waitcnt lgkmcnt(0)
	v_pk_mul_f32 v[32:33], v[36:37], v[88:89] op_sel_hi:[1,0]
	v_add_f32_e32 v36, v73, v89
	ds_bpermute_b32 v37, v133, v36
	v_pk_mul_f32 v[34:35], v[38:39], v[88:89] op_sel_hi:[1,0]
	v_cvt_pk_bf16_f32 v32, v32, v33
	v_cvt_pk_bf16_f32 v33, v34, v35
	global_store_dwordx2 v[86:87], v[32:33], off offset:3072 sc1
	s_waitcnt lgkmcnt(0)
	v_add_f32_e32 v36, v36, v37
	ds_bpermute_b32 v37, v134, v36
	v_pk_mul_f32 v[32:33], v[40:41], v[88:89] op_sel_hi:[1,0]
	v_pk_mul_f32 v[34:35], v[42:43], v[88:89] op_sel_hi:[1,0]
	v_cvt_pk_bf16_f32 v32, v32, v33
	v_cvt_pk_bf16_f32 v33, v34, v35
	s_waitcnt lgkmcnt(0)
	v_add_f32_e32 v34, v36, v37
	ds_bpermute_b32 v35, v135, v34
	global_store_dwordx2 v[86:87], v[32:33], off offset:3584 sc1
	v_lshl_add_u64 v[32:33], v[76:77], 0, v[92:93]
	global_store_dwordx4 v[32:33], v[44:47], off nt sc1
	global_store_dwordx4 v[32:33], v[48:51], off offset:1024 nt sc1
	global_store_dwordx4 v[32:33], v[52:55], off offset:2048 nt sc1
	global_store_dwordx4 v[32:33], v[56:59], off offset:3072 nt sc1
	v_add_co_u32_e32 v32, vcc, s3, v32
	s_waitcnt lgkmcnt(0)
	v_add_f32_e32 v34, v34, v35
	ds_bpermute_b32 v35, v136, v34
	v_addc_co_u32_e32 v33, vcc, 0, v33, vcc
	global_store_dwordx4 v[32:33], v[60:63], off nt sc1
	global_store_dwordx4 v[32:33], v[94:97], off offset:1024 nt sc1
	global_store_dwordx4 v[32:33], v[68:71], off offset:2048 nt sc1
	global_store_dwordx4 v[32:33], v[64:67], off offset:3072 nt sc1
	s_waitcnt lgkmcnt(0)
	v_add_f32_e32 v34, v34, v35
	v_fmamk_f32 v34, v34, 0x3a000000, v82
	v_mul_f32_e32 v35, 0x4b800000, v34
	v_cmp_gt_f32_e32 vcc, s14, v34
	s_nop 1
	v_cndmask_b32_e32 v34, v34, v35, vcc
	v_rsq_f32_e32 v34, v34
	s_nop 0
	v_mul_f32_e32 v32, 0x45800000, v34
	v_cndmask_b32_e32 v32, v34, v32, vcc
	v_pk_mul_f32 v[36:37], v[44:45], v[32:33] op_sel_hi:[1,0]
	v_pk_mul_f32 v[38:39], v[46:47], v[32:33] op_sel_hi:[1,0]
	v_lshl_add_u64 v[34:35], v[78:79], 0, v[84:85]
	v_cvt_pk_bf16_f32 v36, v36, v37
	v_cvt_pk_bf16_f32 v37, v38, v39
	global_store_dwordx2 v[34:35], v[36:37], off sc1
	v_pk_mul_f32 v[36:37], v[48:49], v[32:33] op_sel_hi:[1,0]
	v_pk_mul_f32 v[38:39], v[50:51], v[32:33] op_sel_hi:[1,0]
	v_cvt_pk_bf16_f32 v36, v36, v37
	v_cvt_pk_bf16_f32 v37, v38, v39
	global_store_dwordx2 v[34:35], v[36:37], off offset:512 sc1
	v_pk_mul_f32 v[36:37], v[52:53], v[32:33] op_sel_hi:[1,0]
	v_pk_mul_f32 v[38:39], v[54:55], v[32:33] op_sel_hi:[1,0]
	v_cvt_pk_bf16_f32 v36, v36, v37
	v_cvt_pk_bf16_f32 v37, v38, v39
	global_store_dwordx2 v[34:35], v[36:37], off offset:1024 sc1
	v_pk_mul_f32 v[36:37], v[56:57], v[32:33] op_sel_hi:[1,0]
	v_pk_mul_f32 v[38:39], v[58:59], v[32:33] op_sel_hi:[1,0]
	v_cvt_pk_bf16_f32 v36, v36, v37
	v_cvt_pk_bf16_f32 v37, v38, v39
	global_store_dwordx2 v[34:35], v[36:37], off offset:1536 sc1
	v_pk_mul_f32 v[36:37], v[60:61], v[32:33] op_sel_hi:[1,0]
	v_pk_mul_f32 v[38:39], v[62:63], v[32:33] op_sel_hi:[1,0]
	v_cvt_pk_bf16_f32 v36, v36, v37
	v_cvt_pk_bf16_f32 v37, v38, v39
	global_store_dwordx2 v[34:35], v[36:37], off offset:2048 sc1
	v_pk_mul_f32 v[36:37], v[94:95], v[32:33] op_sel_hi:[1,0]
	v_pk_mul_f32 v[38:39], v[96:97], v[32:33] op_sel_hi:[1,0]
	v_cvt_pk_bf16_f32 v36, v36, v37
	v_cvt_pk_bf16_f32 v37, v38, v39
	global_store_dwordx2 v[34:35], v[36:37], off offset:2560 sc1
	v_pk_mul_f32 v[36:37], v[68:69], v[32:33] op_sel_hi:[1,0]
	v_pk_mul_f32 v[38:39], v[70:71], v[32:33] op_sel_hi:[1,0]
	v_cvt_pk_bf16_f32 v36, v36, v37
	v_cvt_pk_bf16_f32 v37, v38, v39
	global_store_dwordx2 v[34:35], v[36:37], off offset:3072 sc1
	v_pk_mul_f32 v[36:37], v[64:65], v[32:33] op_sel_hi:[1,0]
	v_pk_mul_f32 v[32:33], v[66:67], v[32:33] op_sel_hi:[1,0]
	v_cmp_lt_i32_e32 vcc, s15, v72
	v_cvt_pk_bf16_f32 v36, v36, v37
	v_cvt_pk_bf16_f32 v37, v32, v33
	s_or_b64 s[10:11], vcc, s[10:11]
	global_store_dwordx2 v[34:35], v[36:37], off offset:3584 sc1
	s_andn2_b64 exec, exec, s[10:11]
	s_cbranch_execnz .LBB0_756

.LBB0_971:
	s_andn2_saveexec_b64 s[8:9], s[24:25]
	v_mul_f32_e64 v2, |v1|, s39
	v_rndne_f32_e32 v22, v2
	v_cvt_i32_f32_e32 v21, v22
	v_fma_f32 v2, v22, s52, |v1|
	v_fmac_f32_e32 v2, 0xb3a22168, v22
	v_fmac_f32_e32 v2, 0xa7c234c4, v22
	s_or_b64 exec, exec, s[8:9]
	v_mul_f32_e32 v23, v2, v2
	v_fmamk_f32 v24, v23, 0xb94c1982, v43
	v_fmaak_f32 v24, v23, v24, 0xbe2aaa9d
	v_mul_f32_e32 v24, v23, v24
	v_fmac_f32_e32 v2, v2, v24
	v_fmamk_f32 v24, v23, 0x37d75334, v44
	v_fmaak_f32 v24, v23, v24, 0x3d2aabf7
	v_fmaak_f32 v24, v23, v24, 0xbf000004
	v_fma_f32 v23, v23, v24, 1.0
	v_lshlrev_b32_e32 v24, 30, v21
	v_and_b32_e32 v21, 1, v21
	v_cmp_eq_u32_e32 vcc, 0, v21
	v_xor_b32_e32 v20, v20, v1
	v_and_b32_e32 v25, 0x80000000, v24
	v_cndmask_b32_e32 v21, v23, v2, vcc
	v_xor_b32_e32 v20, v20, v21
	v_xor_b32_e32 v2, 0x80000000, v2
	v_xor_b32_e32 v20, v20, v25
	v_cndmask_b32_e32 v2, v2, v23, vcc
	v_cmp_class_f32_e64 vcc, v1, s54
	v_lshlrev_b32_e32 v22, 16, v47
	v_bitop3_b32 v2, v2, v24, s53 bitop3:0x78
	v_cndmask_b32_e32 v29, v46, v20, vcc
	v_lshlrev_b32_e32 v17, 16, v17
	v_cndmask_b32_e32 v28, v46, v2, vcc
	v_mul_f32_e32 v1, v29, v22
	v_fma_f32 v2, v28, v17, -v1
	v_mul_f32_e32 v1, v29, v17
	v_fmac_f32_e32 v1, v28, v22
	v_lshlrev_b64 v[24:25], 7, v[18:19]
	ds_bpermute_b32 v17, v40, v2
	ds_bpermute_b32 v19, v41, v2
	ds_bpermute_b32 v20, v42, v2
	ds_bpermute_b32 v21, v40, v1
	ds_bpermute_b32 v22, v41, v1
	ds_bpermute_b32 v23, v42, v1
	v_lshl_or_b32 v24, v212, 2, v24
	v_lshl_add_u64 v[26:27], s[48:49], 0, v[24:25]
	v_lshl_add_u64 v[24:25], s[50:51], 0, v[24:25]
	global_store_dword v[26:27], v28, off sc1
	global_store_dword v[24:25], v29, off sc1
	s_and_saveexec_b64 s[8:9], s[6:7]
	s_cbranch_execz .LBB0_968
	s_waitcnt lgkmcnt(3)
	v_cvt_pk_bf16_f32 v25, v19, v20
	s_waitcnt lgkmcnt(2)
	v_cvt_pk_bf16_f32 v26, v1, v21
	v_mov_b64_e32 v[20:21], s[42:43]
	v_cvt_pk_bf16_f32 v24, v2, v17
	v_mad_i64_i32 v[18:19], s[10:11], v18, s55, v[20:21]
	v_mov_b32_e32 v17, v3
	v_lshl_add_u64 v[18:19], v[18:19], 0, v[16:17]
	v_add_co_u32_e32 v20, vcc, s56, v18
	s_waitcnt lgkmcnt(0)
	v_cvt_pk_bf16_f32 v27, v22, v23
	v_addc_co_u32_e32 v21, vcc, 0, v19, vcc
	v_add_co_u32_e32 v18, vcc, 0x19005000, v18
	global_store_dwordx4 v[20:21], v[24:27], off offset:256 sc1
	global_store_dwordx4 v[20:21], v[24:27], off offset:640 sc1
	global_store_dwordx4 v[20:21], v[24:27], off offset:1024 sc1
	global_store_dwordx4 v[20:21], v[24:27], off offset:1408 sc1
	global_store_dwordx4 v[20:21], v[24:27], off offset:1792 sc1
	global_store_dwordx4 v[20:21], v[24:27], off offset:2176 sc1
	global_store_dwordx4 v[20:21], v[24:27], off offset:2560 sc1
	global_store_dwordx4 v[20:21], v[24:27], off offset:2944 sc1
	global_store_dwordx4 v[20:21], v[24:27], off offset:3328 sc1
	global_store_dwordx4 v[20:21], v[24:27], off offset:3712 sc1
	v_addc_co_u32_e32 v19, vcc, 0, v19, vcc
	global_store_dwordx4 v[18:19], v[24:27], off sc1
	global_store_dwordx4 v[18:19], v[24:27], off offset:384 sc1
	s_branch .LBB0_968
